# P0 fast path (pipelined, nt loads) + XB8 scratch moved from d_out to unused d_ws region + nt on P4 residual loads
# baseline (speedup 1.0000x reference)
; __device__ __forceinline__ unsigned cvt_pk_bf16(float lo, float hi) { unsigned r; asm volatile("v_cvt_pk_bf16_f32 %0, %1, %2" : "=v"(r) : "v"(lo), "v"(hi)); return r; }
; __global__ void __launch_bounds__(512, 2) hybrid_fwd(Args a) {
;     ...
;         const size_t gt = (size_t)bx * 512 + tid, GT = (size_t)G * 512;
;         {
;             const size_t NCH = (size_t)M * D / 8;
;             for (size_t i0 = gt; i0 < NCH; i0 += 4 * GT) {
;                 f32x4 v[4][2];
; #pragma unroll
;                 for (int u = 0; u < 4; ++u) { const size_t i = i0 + (size_t)u * GT; if (i < NCH) { v[u][0] = ((const f32x4*)a.x)[2 * i]; v[u][1] = ((const f32x4*)a.x)[2 * i + 1]; } }
; #pragma unroll
;                 for (int u = 0; u < 4; ++u) { const size_t i = i0 + (size_t)u * GT; if (i < NCH) {
;                     u32x4 w; w.x = cvt_pk_bf16(v[u][0][0], v[u][0][1]); w.y = cvt_pk_bf16(v[u][0][2], v[u][0][3]); w.z = cvt_pk_bf16(v[u][1][0], v[u][1][1]); w.w = cvt_pk_bf16(v[u][1][2], v[u][1][3]);
;                     if (a.n_bf16 > 0) ((u32x4*)XB)[i] = w;
;                     const unsigned p0 = pack_fp8x4(v[u][0][0], v[u][0][1], v[u][0][2], v[u][0][3]), p1 = pack_fp8x4(v[u][1][0], v[u][1][1], v[u][1][2], v[u][1][3]);
;                     ((u32x2*)XB8)[i] = (u32x2){p0, p1}; } }
.LBB0_2:
	s_or_b64 exec, exec, s[4:5]
	s_ashr_i32 s3, s2, 31
	s_lshl_b64 s[4:5], s[2:3], 9
	v_mov_b32_e32 v161, 0
	v_lshl_add_u64 v[38:39], s[4:5], 0, v[160:161]
	s_waitcnt lgkmcnt(0)
	s_ashr_i32 s93, s92, 31
	s_mov_b64 s[12:13], 0x400000
	s_lshl_b64 s[14:15], s[92:93], 9
	v_cmp_gt_u64_e32 vcc, s[12:13], v[38:39]
	v_lshlrev_b32_e32 v40, 3, v160
	s_mov_b32 s100, 0
	s_cmp_lg_u32 s92, 0x100
	s_cbranch_scc1 .Lp0_done
	s_load_dword s16, s[70:71], 0x1c0
	s_load_dwordx2 s[18:19], s[70:71], 0x1c8
	s_load_dwordx2 s[6:7], s[70:71], 0x0
	s_load_dwordx2 s[20:21], s[70:71], 0x8
	s_load_dwordx2 s[22:23], s[70:71], 0x10
	s_waitcnt lgkmcnt(0)
	s_cmp_lg_u32 s16, 0
	s_cbranch_scc1 .Lp0_done
	s_cmp_lg_u32 s18, -1
	s_cbranch_scc1 .Lp0_done
	s_cmpk_lg_u32 s19, 0x1fff
	s_cbranch_scc1 .Lp0_done
	v_lshl_add_u32 v1, s2, 9, v160
	v_and_b32_e32 v4, 63, v160
	v_lshlrev_b32_e32 v2, 5, v1
	v_lshlrev_b32_e32 v3, 3, v1
	s_add_u32 s8, s90, 0x2000000
	s_addc_u32 s9, s91, 0
	global_load_dwordx4 v[64:67], v2, s[6:7] nt
	global_load_dwordx4 v[68:71], v2, s[6:7] offset:16 nt
	s_add_u32 s6, s6, 0x400000
	s_addc_u32 s7, s7, 0
	global_load_dwordx4 v[72:75], v2, s[6:7] nt
	global_load_dwordx4 v[76:79], v2, s[6:7] offset:16 nt
	s_add_u32 s6, s6, 0x400000
	s_addc_u32 s7, s7, 0
	global_load_dwordx4 v[80:83], v2, s[6:7] nt
	global_load_dwordx4 v[84:87], v2, s[6:7] offset:16 nt
	s_add_u32 s6, s6, 0x400000
	s_addc_u32 s7, s7, 0
	global_load_dwordx4 v[88:91], v2, s[6:7] nt
	global_load_dwordx4 v[92:95], v2, s[6:7] offset:16 nt
	s_add_u32 s6, s6, 0x400000
	s_addc_u32 s7, s7, 0
	global_load_dwordx4 v[96:99], v2, s[6:7] nt
	global_load_dwordx4 v[100:103], v2, s[6:7] offset:16 nt
	s_add_u32 s6, s6, 0x400000
	s_addc_u32 s7, s7, 0
	global_load_dwordx4 v[104:107], v2, s[6:7] nt
	global_load_dwordx4 v[108:111], v2, s[6:7] offset:16 nt
	s_add_u32 s6, s6, 0x400000
	s_addc_u32 s7, s7, 0
	global_load_dwordx4 v[112:115], v2, s[6:7] nt
	global_load_dwordx4 v[116:119], v2, s[6:7] offset:16 nt
	s_add_u32 s6, s6, 0x400000
	s_addc_u32 s7, s7, 0
	global_load_dwordx4 v[120:123], v2, s[6:7] nt
	global_load_dwordx4 v[124:127], v2, s[6:7] offset:16 nt
	s_add_u32 s6, s6, 0x400000
	s_addc_u32 s7, s7, 0
	s_waitcnt vmcnt(14)
	v_cvt_pk_fp8_f32 v8, v64, v65
	v_cvt_pk_fp8_f32 v9, v66, v67
	v_cvt_pk_fp8_f32 v10, v68, v69
	v_cvt_pk_fp8_f32 v11, v70, v71
	v_and_b32_e32 v8, 0xffff, v8
	v_and_b32_e32 v10, 0xffff, v10
	v_lshl_or_b32 v128, v9, 16, v8
	v_lshl_or_b32 v129, v11, 16, v10
	global_store_dwordx2 v3, v[128:129], s[8:9]
	s_add_u32 s8, s8, 0x100000
	s_addc_u32 s9, s9, 0
	global_load_dwordx4 v[64:67], v2, s[6:7] nt
	global_load_dwordx4 v[68:71], v2, s[6:7] offset:16 nt
	s_add_u32 s6, s6, 0x400000
	s_addc_u32 s7, s7, 0
	s_waitcnt vmcnt(15)
	v_cvt_pk_fp8_f32 v8, v72, v73
	v_cvt_pk_fp8_f32 v9, v74, v75
	v_cvt_pk_fp8_f32 v10, v76, v77
	v_cvt_pk_fp8_f32 v11, v78, v79
	v_and_b32_e32 v8, 0xffff, v8
	v_and_b32_e32 v10, 0xffff, v10
	v_lshl_or_b32 v130, v9, 16, v8
	v_lshl_or_b32 v131, v11, 16, v10
	global_store_dwordx2 v3, v[130:131], s[8:9]
	s_add_u32 s8, s8, 0x100000
	s_addc_u32 s9, s9, 0
	global_load_dwordx4 v[72:75], v2, s[6:7] nt
	global_load_dwordx4 v[76:79], v2, s[6:7] offset:16 nt
	s_add_u32 s6, s6, 0x400000
	s_addc_u32 s7, s7, 0
	s_waitcnt vmcnt(16)
	v_cvt_pk_fp8_f32 v8, v80, v81
	v_cvt_pk_fp8_f32 v9, v82, v83
	v_cvt_pk_fp8_f32 v10, v84, v85
	v_cvt_pk_fp8_f32 v11, v86, v87
	v_and_b32_e32 v8, 0xffff, v8
	v_and_b32_e32 v10, 0xffff, v10
	v_lshl_or_b32 v132, v9, 16, v8
	v_lshl_or_b32 v133, v11, 16, v10
	global_store_dwordx2 v3, v[132:133], s[8:9]
	s_add_u32 s8, s8, 0x100000
	s_addc_u32 s9, s9, 0
	global_load_dwordx4 v[80:83], v2, s[6:7] nt
	global_load_dwordx4 v[84:87], v2, s[6:7] offset:16 nt
	s_add_u32 s6, s6, 0x400000
	s_addc_u32 s7, s7, 0
	s_waitcnt vmcnt(17)
	v_cvt_pk_fp8_f32 v8, v88, v89
	v_cvt_pk_fp8_f32 v9, v90, v91
	v_cvt_pk_fp8_f32 v10, v92, v93
	v_cvt_pk_fp8_f32 v11, v94, v95
	v_and_b32_e32 v8, 0xffff, v8
	v_and_b32_e32 v10, 0xffff, v10
	v_lshl_or_b32 v134, v9, 16, v8
	v_lshl_or_b32 v135, v11, 16, v10
	global_store_dwordx2 v3, v[134:135], s[8:9]
	s_add_u32 s8, s8, 0x100000
	s_addc_u32 s9, s9, 0
	global_load_dwordx4 v[88:91], v2, s[6:7] nt
	global_load_dwordx4 v[92:95], v2, s[6:7] offset:16 nt
	s_add_u32 s6, s6, 0x400000
	s_addc_u32 s7, s7, 0
	s_waitcnt vmcnt(18)
	v_cvt_pk_fp8_f32 v8, v96, v97
	v_cvt_pk_fp8_f32 v9, v98, v99
	v_cvt_pk_fp8_f32 v10, v100, v101
	v_cvt_pk_fp8_f32 v11, v102, v103
	v_and_b32_e32 v8, 0xffff, v8
	v_and_b32_e32 v10, 0xffff, v10
	v_lshl_or_b32 v136, v9, 16, v8
	v_lshl_or_b32 v137, v11, 16, v10
	global_store_dwordx2 v3, v[136:137], s[8:9]
	s_add_u32 s8, s8, 0x100000
	s_addc_u32 s9, s9, 0
	global_load_dwordx4 v[96:99], v2, s[6:7] nt
	global_load_dwordx4 v[100:103], v2, s[6:7] offset:16 nt
	s_add_u32 s6, s6, 0x400000
	s_addc_u32 s7, s7, 0
	s_waitcnt vmcnt(19)
	v_cvt_pk_fp8_f32 v8, v104, v105
	v_cvt_pk_fp8_f32 v9, v106, v107
	v_cvt_pk_fp8_f32 v10, v108, v109
	v_cvt_pk_fp8_f32 v11, v110, v111
	v_and_b32_e32 v8, 0xffff, v8
	v_and_b32_e32 v10, 0xffff, v10
	v_lshl_or_b32 v138, v9, 16, v8
	v_lshl_or_b32 v139, v11, 16, v10
	global_store_dwordx2 v3, v[138:139], s[8:9]
	s_add_u32 s8, s8, 0x100000
	s_addc_u32 s9, s9, 0
	global_load_dwordx4 v[104:107], v2, s[6:7] nt
	global_load_dwordx4 v[108:111], v2, s[6:7] offset:16 nt
	s_add_u32 s6, s6, 0x400000
	s_addc_u32 s7, s7, 0
	s_waitcnt vmcnt(20)
	v_cvt_pk_fp8_f32 v8, v112, v113
	v_cvt_pk_fp8_f32 v9, v114, v115
	v_cvt_pk_fp8_f32 v10, v116, v117
	v_cvt_pk_fp8_f32 v11, v118, v119
	v_and_b32_e32 v8, 0xffff, v8
	v_and_b32_e32 v10, 0xffff, v10
	v_lshl_or_b32 v140, v9, 16, v8
	v_lshl_or_b32 v141, v11, 16, v10
	global_store_dwordx2 v3, v[140:141], s[8:9]
	s_add_u32 s8, s8, 0x100000
	s_addc_u32 s9, s9, 0
	global_load_dwordx4 v[112:115], v2, s[6:7] nt
	global_load_dwordx4 v[116:119], v2, s[6:7] offset:16 nt
	s_add_u32 s6, s6, 0x400000
	s_addc_u32 s7, s7, 0
	s_waitcnt vmcnt(21)
; __device__ __forceinline__ unsigned cvt_pk_bf16(float lo, float hi) { unsigned r; asm volatile("v_cvt_pk_bf16_f32 %0, %1, %2" : "=v"(r) : "v"(lo), "v"(hi)); return r; }
; __global__ void __launch_bounds__(512, 2) hybrid_fwd(Args a) {
;     ...
;             for (size_t i0 = gt; i0 < NCH; i0 += 4 * GT) {
;                 f32x4 v[4][2];
; #pragma unroll
;                 for (int u = 0; u < 4; ++u) { const size_t i = i0 + (size_t)u * GT; if (i < NCH) { v[u][0] = ((const f32x4*)a.x)[2 * i]; v[u][1] = ((const f32x4*)a.x)[2 * i + 1]; } }
; #pragma unroll
;                 for (int u = 0; u < 4; ++u) { const size_t i = i0 + (size_t)u * GT; if (i < NCH) {
;                     u32x4 w; w.x = cvt_pk_bf16(v[u][0][0], v[u][0][1]); w.y = cvt_pk_bf16(v[u][0][2], v[u][0][3]); w.z = cvt_pk_bf16(v[u][1][0], v[u][1][1]); w.w = cvt_pk_bf16(v[u][1][2], v[u][1][3]);
;                     if (a.n_bf16 > 0) ((u32x4*)XB)[i] = w;
;                     const unsigned p0 = pack_fp8x4(v[u][0][0], v[u][0][1], v[u][0][2], v[u][0][3]), p1 = pack_fp8x4(v[u][1][0], v[u][1][1], v[u][1][2], v[u][1][3]);
;                     ((u32x2*)XB8)[i] = (u32x2){p0, p1}; } }
	v_cvt_pk_fp8_f32 v8, v120, v121
	v_cvt_pk_fp8_f32 v9, v122, v123
	v_cvt_pk_fp8_f32 v10, v124, v125
	v_cvt_pk_fp8_f32 v11, v126, v127
	v_and_b32_e32 v8, 0xffff, v8
	v_and_b32_e32 v10, 0xffff, v10
	v_lshl_or_b32 v142, v9, 16, v8
	v_lshl_or_b32 v143, v11, 16, v10
	global_store_dwordx2 v3, v[142:143], s[8:9]
	s_add_u32 s8, s8, 0x100000
	s_addc_u32 s9, s9, 0
	global_load_dwordx4 v[120:123], v2, s[6:7] nt
	global_load_dwordx4 v[124:127], v2, s[6:7] offset:16 nt
	s_add_u32 s6, s6, 0x400000
	s_addc_u32 s7, s7, 0
	s_waitcnt vmcnt(21)
	v_cvt_pk_fp8_f32 v8, v64, v65
	v_cvt_pk_fp8_f32 v9, v66, v67
	v_cvt_pk_fp8_f32 v10, v68, v69
	v_cvt_pk_fp8_f32 v11, v70, v71
	v_and_b32_e32 v8, 0xffff, v8
	v_and_b32_e32 v10, 0xffff, v10
	v_lshl_or_b32 v128, v9, 16, v8
	v_lshl_or_b32 v129, v11, 16, v10
	global_store_dwordx2 v3, v[128:129], s[8:9]
	s_add_u32 s8, s8, 0x100000
	s_addc_u32 s9, s9, 0
	global_load_dwordx4 v[64:67], v2, s[6:7] nt
	global_load_dwordx4 v[68:71], v2, s[6:7] offset:16 nt
	s_add_u32 s6, s6, 0x400000
	s_addc_u32 s7, s7, 0
	s_waitcnt vmcnt(21)
	v_cvt_pk_fp8_f32 v8, v72, v73
	v_cvt_pk_fp8_f32 v9, v74, v75
	v_cvt_pk_fp8_f32 v10, v76, v77
	v_cvt_pk_fp8_f32 v11, v78, v79
	v_and_b32_e32 v8, 0xffff, v8
	v_and_b32_e32 v10, 0xffff, v10
	v_lshl_or_b32 v130, v9, 16, v8
	v_lshl_or_b32 v131, v11, 16, v10
	global_store_dwordx2 v3, v[130:131], s[8:9]
	s_add_u32 s8, s8, 0x100000
	s_addc_u32 s9, s9, 0
	global_load_dwordx4 v[72:75], v2, s[6:7] nt
	global_load_dwordx4 v[76:79], v2, s[6:7] offset:16 nt
	s_add_u32 s6, s6, 0x400000
	s_addc_u32 s7, s7, 0
	s_waitcnt vmcnt(21)
	v_cvt_pk_fp8_f32 v8, v80, v81
	v_cvt_pk_fp8_f32 v9, v82, v83
	v_cvt_pk_fp8_f32 v10, v84, v85
	v_cvt_pk_fp8_f32 v11, v86, v87
	v_and_b32_e32 v8, 0xffff, v8
	v_and_b32_e32 v10, 0xffff, v10
	v_lshl_or_b32 v132, v9, 16, v8
	v_lshl_or_b32 v133, v11, 16, v10
	global_store_dwordx2 v3, v[132:133], s[8:9]
	s_add_u32 s8, s8, 0x100000
	s_addc_u32 s9, s9, 0
	global_load_dwordx4 v[80:83], v2, s[6:7] nt
	global_load_dwordx4 v[84:87], v2, s[6:7] offset:16 nt
	s_add_u32 s6, s6, 0x400000
	s_addc_u32 s7, s7, 0
	s_waitcnt vmcnt(21)
	v_cvt_pk_fp8_f32 v8, v88, v89
	v_cvt_pk_fp8_f32 v9, v90, v91
	v_cvt_pk_fp8_f32 v10, v92, v93
	v_cvt_pk_fp8_f32 v11, v94, v95
	v_and_b32_e32 v8, 0xffff, v8
	v_and_b32_e32 v10, 0xffff, v10
	v_lshl_or_b32 v134, v9, 16, v8
	v_lshl_or_b32 v135, v11, 16, v10
	global_store_dwordx2 v3, v[134:135], s[8:9]
	s_add_u32 s8, s8, 0x100000
	s_addc_u32 s9, s9, 0
	global_load_dwordx4 v[88:91], v2, s[6:7] nt
	global_load_dwordx4 v[92:95], v2, s[6:7] offset:16 nt
	s_add_u32 s6, s6, 0x400000
	s_addc_u32 s7, s7, 0
	s_waitcnt vmcnt(21)
	v_cvt_pk_fp8_f32 v8, v96, v97
	v_cvt_pk_fp8_f32 v9, v98, v99
	v_cvt_pk_fp8_f32 v10, v100, v101
	v_cvt_pk_fp8_f32 v11, v102, v103
	v_and_b32_e32 v8, 0xffff, v8
	v_and_b32_e32 v10, 0xffff, v10
	v_lshl_or_b32 v136, v9, 16, v8
	v_lshl_or_b32 v137, v11, 16, v10
	global_store_dwordx2 v3, v[136:137], s[8:9]
	s_add_u32 s8, s8, 0x100000
	s_addc_u32 s9, s9, 0
	global_load_dwordx4 v[96:99], v2, s[6:7] nt
	global_load_dwordx4 v[100:103], v2, s[6:7] offset:16 nt
	s_add_u32 s6, s6, 0x400000
	s_addc_u32 s7, s7, 0
	s_waitcnt vmcnt(21)
	v_cvt_pk_fp8_f32 v8, v104, v105
	v_cvt_pk_fp8_f32 v9, v106, v107
	v_cvt_pk_fp8_f32 v10, v108, v109
	v_cvt_pk_fp8_f32 v11, v110, v111
	v_and_b32_e32 v8, 0xffff, v8
	v_and_b32_e32 v10, 0xffff, v10
	v_lshl_or_b32 v138, v9, 16, v8
	v_lshl_or_b32 v139, v11, 16, v10
	global_store_dwordx2 v3, v[138:139], s[8:9]
	s_add_u32 s8, s8, 0x100000
	s_addc_u32 s9, s9, 0
	global_load_dwordx4 v[104:107], v2, s[6:7] nt
	global_load_dwordx4 v[108:111], v2, s[6:7] offset:16 nt
	s_add_u32 s6, s6, 0x400000
	s_addc_u32 s7, s7, 0
	s_waitcnt vmcnt(21)
	v_cvt_pk_fp8_f32 v8, v112, v113
	v_cvt_pk_fp8_f32 v9, v114, v115
	v_cvt_pk_fp8_f32 v10, v116, v117
	v_cvt_pk_fp8_f32 v11, v118, v119
	v_and_b32_e32 v8, 0xffff, v8
	v_and_b32_e32 v10, 0xffff, v10
	v_lshl_or_b32 v140, v9, 16, v8
	v_lshl_or_b32 v141, v11, 16, v10
	global_store_dwordx2 v3, v[140:141], s[8:9]
	s_add_u32 s8, s8, 0x100000
	s_addc_u32 s9, s9, 0
	global_load_dwordx4 v[112:115], v2, s[6:7] nt
	global_load_dwordx4 v[116:119], v2, s[6:7] offset:16 nt
	s_add_u32 s6, s6, 0x400000
	s_addc_u32 s7, s7, 0
	s_waitcnt vmcnt(21)
	v_cvt_pk_fp8_f32 v8, v120, v121
	v_cvt_pk_fp8_f32 v9, v122, v123
	v_cvt_pk_fp8_f32 v10, v124, v125
	v_cvt_pk_fp8_f32 v11, v126, v127
	v_and_b32_e32 v8, 0xffff, v8
	v_and_b32_e32 v10, 0xffff, v10
	v_lshl_or_b32 v142, v9, 16, v8
	v_lshl_or_b32 v143, v11, 16, v10
	global_store_dwordx2 v3, v[142:143], s[8:9]
	s_add_u32 s8, s8, 0x100000
	s_addc_u32 s9, s9, 0
	global_load_dwordx4 v[120:123], v2, s[6:7] nt
	global_load_dwordx4 v[124:127], v2, s[6:7] offset:16 nt
	s_add_u32 s6, s6, 0x400000
	s_addc_u32 s7, s7, 0
	s_waitcnt vmcnt(21)
	v_cvt_pk_fp8_f32 v8, v64, v65
	v_cvt_pk_fp8_f32 v9, v66, v67
	v_cvt_pk_fp8_f32 v10, v68, v69
	v_cvt_pk_fp8_f32 v11, v70, v71
	v_and_b32_e32 v8, 0xffff, v8
	v_and_b32_e32 v10, 0xffff, v10
	v_lshl_or_b32 v128, v9, 16, v8
	v_lshl_or_b32 v129, v11, 16, v10
	global_store_dwordx2 v3, v[128:129], s[8:9]
	s_add_u32 s8, s8, 0x100000
	s_addc_u32 s9, s9, 0
	global_load_dwordx4 v[64:67], v2, s[6:7] nt
	global_load_dwordx4 v[68:71], v2, s[6:7] offset:16 nt
	s_add_u32 s6, s6, 0x400000
	s_addc_u32 s7, s7, 0
	s_waitcnt vmcnt(21)
	v_cvt_pk_fp8_f32 v8, v72, v73
	v_cvt_pk_fp8_f32 v9, v74, v75
	v_cvt_pk_fp8_f32 v10, v76, v77
	v_cvt_pk_fp8_f32 v11, v78, v79
	v_and_b32_e32 v8, 0xffff, v8
	v_and_b32_e32 v10, 0xffff, v10
	v_lshl_or_b32 v130, v9, 16, v8
	v_lshl_or_b32 v131, v11, 16, v10
	global_store_dwordx2 v3, v[130:131], s[8:9]
	s_add_u32 s8, s8, 0x100000
	s_addc_u32 s9, s9, 0
	global_load_dwordx4 v[72:75], v2, s[6:7] nt
	global_load_dwordx4 v[76:79], v2, s[6:7] offset:16 nt
	s_add_u32 s6, s6, 0x400000
	s_addc_u32 s7, s7, 0
	s_waitcnt vmcnt(21)
; __device__ __forceinline__ unsigned cvt_pk_bf16(float lo, float hi) { unsigned r; asm volatile("v_cvt_pk_bf16_f32 %0, %1, %2" : "=v"(r) : "v"(lo), "v"(hi)); return r; }
; __global__ void __launch_bounds__(512, 2) hybrid_fwd(Args a) {
;     ...
;             for (size_t i0 = gt; i0 < NCH; i0 += 4 * GT) {
;                 f32x4 v[4][2];
; #pragma unroll
;                 for (int u = 0; u < 4; ++u) { const size_t i = i0 + (size_t)u * GT; if (i < NCH) { v[u][0] = ((const f32x4*)a.x)[2 * i]; v[u][1] = ((const f32x4*)a.x)[2 * i + 1]; } }
; #pragma unroll
;                 for (int u = 0; u < 4; ++u) { const size_t i = i0 + (size_t)u * GT; if (i < NCH) {
;                     u32x4 w; w.x = cvt_pk_bf16(v[u][0][0], v[u][0][1]); w.y = cvt_pk_bf16(v[u][0][2], v[u][0][3]); w.z = cvt_pk_bf16(v[u][1][0], v[u][1][1]); w.w = cvt_pk_bf16(v[u][1][2], v[u][1][3]);
;                     if (a.n_bf16 > 0) ((u32x4*)XB)[i] = w;
;                     const unsigned p0 = pack_fp8x4(v[u][0][0], v[u][0][1], v[u][0][2], v[u][0][3]), p1 = pack_fp8x4(v[u][1][0], v[u][1][1], v[u][1][2], v[u][1][3]);
;                     ((u32x2*)XB8)[i] = (u32x2){p0, p1}; } }
	v_cvt_pk_fp8_f32 v8, v80, v81
	v_cvt_pk_fp8_f32 v9, v82, v83
	v_cvt_pk_fp8_f32 v10, v84, v85
	v_cvt_pk_fp8_f32 v11, v86, v87
	v_and_b32_e32 v8, 0xffff, v8
	v_and_b32_e32 v10, 0xffff, v10
	v_lshl_or_b32 v132, v9, 16, v8
	v_lshl_or_b32 v133, v11, 16, v10
	global_store_dwordx2 v3, v[132:133], s[8:9]
	s_add_u32 s8, s8, 0x100000
	s_addc_u32 s9, s9, 0
	global_load_dwordx4 v[80:83], v2, s[6:7] nt
	global_load_dwordx4 v[84:87], v2, s[6:7] offset:16 nt
	s_add_u32 s6, s6, 0x400000
	s_addc_u32 s7, s7, 0
	s_waitcnt vmcnt(21)
	v_cvt_pk_fp8_f32 v8, v88, v89
	v_cvt_pk_fp8_f32 v9, v90, v91
	v_cvt_pk_fp8_f32 v10, v92, v93
	v_cvt_pk_fp8_f32 v11, v94, v95
	v_and_b32_e32 v8, 0xffff, v8
	v_and_b32_e32 v10, 0xffff, v10
	v_lshl_or_b32 v134, v9, 16, v8
	v_lshl_or_b32 v135, v11, 16, v10
	global_store_dwordx2 v3, v[134:135], s[8:9]
	s_add_u32 s8, s8, 0x100000
	s_addc_u32 s9, s9, 0
	global_load_dwordx4 v[88:91], v2, s[6:7] nt
	global_load_dwordx4 v[92:95], v2, s[6:7] offset:16 nt
	s_add_u32 s6, s6, 0x400000
	s_addc_u32 s7, s7, 0
	s_waitcnt vmcnt(21)
	v_cvt_pk_fp8_f32 v8, v96, v97
	v_cvt_pk_fp8_f32 v9, v98, v99
	v_cvt_pk_fp8_f32 v10, v100, v101
	v_cvt_pk_fp8_f32 v11, v102, v103
	v_and_b32_e32 v8, 0xffff, v8
	v_and_b32_e32 v10, 0xffff, v10
	v_lshl_or_b32 v136, v9, 16, v8
	v_lshl_or_b32 v137, v11, 16, v10
	global_store_dwordx2 v3, v[136:137], s[8:9]
	s_add_u32 s8, s8, 0x100000
	s_addc_u32 s9, s9, 0
	global_load_dwordx4 v[96:99], v2, s[6:7] nt
	global_load_dwordx4 v[100:103], v2, s[6:7] offset:16 nt
	s_add_u32 s6, s6, 0x400000
	s_addc_u32 s7, s7, 0
	s_waitcnt vmcnt(21)
	v_cvt_pk_fp8_f32 v8, v104, v105
	v_cvt_pk_fp8_f32 v9, v106, v107
	v_cvt_pk_fp8_f32 v10, v108, v109
	v_cvt_pk_fp8_f32 v11, v110, v111
	v_and_b32_e32 v8, 0xffff, v8
	v_and_b32_e32 v10, 0xffff, v10
	v_lshl_or_b32 v138, v9, 16, v8
	v_lshl_or_b32 v139, v11, 16, v10
	global_store_dwordx2 v3, v[138:139], s[8:9]
	s_add_u32 s8, s8, 0x100000
	s_addc_u32 s9, s9, 0
	global_load_dwordx4 v[104:107], v2, s[6:7] nt
	global_load_dwordx4 v[108:111], v2, s[6:7] offset:16 nt
	s_add_u32 s6, s6, 0x400000
	s_addc_u32 s7, s7, 0
	s_waitcnt vmcnt(21)
	v_cvt_pk_fp8_f32 v8, v112, v113
	v_cvt_pk_fp8_f32 v9, v114, v115
	v_cvt_pk_fp8_f32 v10, v116, v117
	v_cvt_pk_fp8_f32 v11, v118, v119
	v_and_b32_e32 v8, 0xffff, v8
	v_and_b32_e32 v10, 0xffff, v10
	v_lshl_or_b32 v140, v9, 16, v8
	v_lshl_or_b32 v141, v11, 16, v10
	global_store_dwordx2 v3, v[140:141], s[8:9]
	s_add_u32 s8, s8, 0x100000
	s_addc_u32 s9, s9, 0
	global_load_dwordx4 v[112:115], v2, s[6:7] nt
	global_load_dwordx4 v[116:119], v2, s[6:7] offset:16 nt
	s_add_u32 s6, s6, 0x400000
	s_addc_u32 s7, s7, 0
	s_waitcnt vmcnt(21)
	v_cvt_pk_fp8_f32 v8, v120, v121
	v_cvt_pk_fp8_f32 v9, v122, v123
	v_cvt_pk_fp8_f32 v10, v124, v125
	v_cvt_pk_fp8_f32 v11, v126, v127
	v_and_b32_e32 v8, 0xffff, v8
	v_and_b32_e32 v10, 0xffff, v10
	v_lshl_or_b32 v142, v9, 16, v8
	v_lshl_or_b32 v143, v11, 16, v10
	global_store_dwordx2 v3, v[142:143], s[8:9]
	s_add_u32 s8, s8, 0x100000
	s_addc_u32 s9, s9, 0
	global_load_dwordx4 v[120:123], v2, s[6:7] nt
	global_load_dwordx4 v[124:127], v2, s[6:7] offset:16 nt
	s_add_u32 s6, s6, 0x400000
	s_addc_u32 s7, s7, 0
	s_waitcnt vmcnt(21)
	v_cvt_pk_fp8_f32 v8, v64, v65
	v_cvt_pk_fp8_f32 v9, v66, v67
	v_cvt_pk_fp8_f32 v10, v68, v69
	v_cvt_pk_fp8_f32 v11, v70, v71
	v_and_b32_e32 v8, 0xffff, v8
	v_and_b32_e32 v10, 0xffff, v10
	v_lshl_or_b32 v128, v9, 16, v8
	v_lshl_or_b32 v129, v11, 16, v10
	global_store_dwordx2 v3, v[128:129], s[8:9]
	s_add_u32 s8, s8, 0x100000
	s_addc_u32 s9, s9, 0
	s_waitcnt vmcnt(19)
	v_cvt_pk_fp8_f32 v8, v72, v73
	v_cvt_pk_fp8_f32 v9, v74, v75
	v_cvt_pk_fp8_f32 v10, v76, v77
	v_cvt_pk_fp8_f32 v11, v78, v79
	v_and_b32_e32 v8, 0xffff, v8
	v_and_b32_e32 v10, 0xffff, v10
	v_lshl_or_b32 v130, v9, 16, v8
	v_lshl_or_b32 v131, v11, 16, v10
	global_store_dwordx2 v3, v[130:131], s[8:9]
	s_add_u32 s8, s8, 0x100000
	s_addc_u32 s9, s9, 0
	s_waitcnt vmcnt(17)
	v_cvt_pk_fp8_f32 v8, v80, v81
	v_cvt_pk_fp8_f32 v9, v82, v83
	v_cvt_pk_fp8_f32 v10, v84, v85
	v_cvt_pk_fp8_f32 v11, v86, v87
	v_and_b32_e32 v8, 0xffff, v8
	v_and_b32_e32 v10, 0xffff, v10
	v_lshl_or_b32 v132, v9, 16, v8
	v_lshl_or_b32 v133, v11, 16, v10
	global_store_dwordx2 v3, v[132:133], s[8:9]
	s_add_u32 s8, s8, 0x100000
	s_addc_u32 s9, s9, 0
	s_waitcnt vmcnt(15)
	v_cvt_pk_fp8_f32 v8, v88, v89
	v_cvt_pk_fp8_f32 v9, v90, v91
	v_cvt_pk_fp8_f32 v10, v92, v93
	v_cvt_pk_fp8_f32 v11, v94, v95
	v_and_b32_e32 v8, 0xffff, v8
	v_and_b32_e32 v10, 0xffff, v10
	v_lshl_or_b32 v134, v9, 16, v8
	v_lshl_or_b32 v135, v11, 16, v10
	global_store_dwordx2 v3, v[134:135], s[8:9]
	s_add_u32 s8, s8, 0x100000
	s_addc_u32 s9, s9, 0
	s_waitcnt vmcnt(13)
	v_cvt_pk_fp8_f32 v8, v96, v97
	v_cvt_pk_fp8_f32 v9, v98, v99
	v_cvt_pk_fp8_f32 v10, v100, v101
	v_cvt_pk_fp8_f32 v11, v102, v103
	v_and_b32_e32 v8, 0xffff, v8
	v_and_b32_e32 v10, 0xffff, v10
	v_lshl_or_b32 v136, v9, 16, v8
	v_lshl_or_b32 v137, v11, 16, v10
	global_store_dwordx2 v3, v[136:137], s[8:9]
	s_add_u32 s8, s8, 0x100000
	s_addc_u32 s9, s9, 0
	s_waitcnt vmcnt(11)
	v_cvt_pk_fp8_f32 v8, v104, v105
	v_cvt_pk_fp8_f32 v9, v106, v107
	v_cvt_pk_fp8_f32 v10, v108, v109
	v_cvt_pk_fp8_f32 v11, v110, v111
	v_and_b32_e32 v8, 0xffff, v8
	v_and_b32_e32 v10, 0xffff, v10
	v_lshl_or_b32 v138, v9, 16, v8
	v_lshl_or_b32 v139, v11, 16, v10
	global_store_dwordx2 v3, v[138:139], s[8:9]
	s_add_u32 s8, s8, 0x100000
	s_addc_u32 s9, s9, 0
	s_waitcnt vmcnt(9)
	v_cvt_pk_fp8_f32 v8, v112, v113
	v_cvt_pk_fp8_f32 v9, v114, v115
	v_cvt_pk_fp8_f32 v10, v116, v117
	v_cvt_pk_fp8_f32 v11, v118, v119
	v_and_b32_e32 v8, 0xffff, v8
	v_and_b32_e32 v10, 0xffff, v10
	v_lshl_or_b32 v140, v9, 16, v8
	v_lshl_or_b32 v141, v11, 16, v10
	global_store_dwordx2 v3, v[140:141], s[8:9]
	s_add_u32 s8, s8, 0x100000
	s_addc_u32 s9, s9, 0
	s_waitcnt vmcnt(7)
; #define LAS __attribute__((address_space(3)))
; __global__ void __launch_bounds__(512, 2) hybrid_fwd(Args a) {
;     ...
;         for (size_t i = gt; i < (size_t)M * 64; i += GT) {
;             const int t = (int)(i >> 6), j = (int)(i & 63);
;             const float ang = (float)a.pos[t] * a.inv_freq[j];
;             const double rev = (double)ang * 0.15915494309189535; const float fr = (float)(rev - __builtin_rint(rev));
;             const f32x2 cs = (f32x2){__builtin_amdgcn_cosf(fr), __builtin_amdgcn_sinf(fr)};
;             csB[i] = cs; if ((j & 1) == 0) csA[(size_t)t * 32 + (j >> 1)] = cs;
;         }
;         LAS float* scr = (LAS float*)(lds + wave * 16384);
;         const int gw = bx * 8 + wave, NGW = G * 8;
;         constexpr int I_IN = (D / 64) * (DIN / 32);
;         for (int it = gw; it < I_IN; it += NGW) { const int nb = it % (DIN / 32), kb = it / (DIN / 32);
;             if ((a.fp8mask >> (nb >> 3)) & 1ull) transpose_item_fp8(a.w_in, DIN, (unsigned char*)WinT, 4096, 0, 64 * kb, gemm_col_to_orig(32 * nb), 32 * nb, W8_SCALE, scr, lane);
	v_cvt_pk_fp8_f32 v8, v120, v121
	v_cvt_pk_fp8_f32 v9, v122, v123
	v_cvt_pk_fp8_f32 v10, v124, v125
	v_cvt_pk_fp8_f32 v11, v126, v127
	v_and_b32_e32 v8, 0xffff, v8
	v_and_b32_e32 v10, 0xffff, v10
	v_lshl_or_b32 v142, v9, 16, v8
	v_lshl_or_b32 v143, v11, 16, v10
	global_store_dwordx2 v3, v[142:143], s[8:9]
	s_add_u32 s8, s8, 0x100000
	s_addc_u32 s9, s9, 0
	s_lshr_b32 s10, s33, 6
	s_lshl_b32 s11, s2, 3
	s_add_u32 s10, s10, s11
	s_lshl_b32 s11, s10, 2
	s_add_u32 s24, s20, s11
	s_addc_u32 s25, s21, 0
	s_load_dword s34, s[24:25], 0x0
	s_load_dword s35, s[24:25], 0x2000
	s_load_dword s36, s[24:25], 0x4000
	s_load_dword s37, s[24:25], 0x6000
	s_load_dword s38, s[24:25], 0x8000
	s_load_dword s39, s[24:25], 0xa000
	s_load_dword s40, s[24:25], 0xc000
	s_load_dword s41, s[24:25], 0xe000
	v_lshlrev_b32_e32 v5, 2, v4
	global_load_dword v5, v5, s[70:71] offset:96
	v_lshlrev_b32_e32 v6, 3, v4
	v_lshrrev_b32_e32 v7, 1, v4
	v_lshlrev_b32_e32 v7, 3, v7
	s_lshl_b32 s11, s10, 9
	s_add_u32 s26, s90, s11
	s_addc_u32 s27, s91, 0
	s_add_u32 s26, s26, 0x7c00000
	s_addc_u32 s27, s27, 0
	s_lshl_b32 s11, s10, 8
	s_add_u32 s28, s90, s11
	s_addc_u32 s29, s91, 0
	s_add_u32 s28, s28, 0x8400000
	s_addc_u32 s29, s29, 0
	s_mov_b32 s42, 0x6dc9c883
	s_mov_b32 s43, 0x3fc45f30
	s_waitcnt vmcnt(0) lgkmcnt(0)
	v_cvt_f32_i32_e32 v16, s34
	v_mul_f32_e32 v16, v5, v16
	v_cvt_f64_f32_e32 v[16:17], v16
	v_mul_f64 v[12:13], v[16:17], s[42:43]
	v_rndne_f64_e32 v[12:13], v[12:13]
	v_fma_f64 v[16:17], v[16:17], s[42:43], -v[12:13]
	v_cvt_f32_f64_e32 v17, v[16:17]
	v_cos_f32_e32 v16, v17
	v_sin_f32_e32 v17, v17
	v_cvt_f32_i32_e32 v18, s35
	v_mul_f32_e32 v18, v5, v18
	v_cvt_f64_f32_e32 v[18:19], v18
	v_mul_f64 v[12:13], v[18:19], s[42:43]
	v_rndne_f64_e32 v[12:13], v[12:13]
	v_fma_f64 v[18:19], v[18:19], s[42:43], -v[12:13]
	v_cvt_f32_f64_e32 v19, v[18:19]
	v_cos_f32_e32 v18, v19
	v_sin_f32_e32 v19, v19
	v_cvt_f32_i32_e32 v20, s36
	v_mul_f32_e32 v20, v5, v20
	v_cvt_f64_f32_e32 v[20:21], v20
	v_mul_f64 v[12:13], v[20:21], s[42:43]
	v_rndne_f64_e32 v[12:13], v[12:13]
	v_fma_f64 v[20:21], v[20:21], s[42:43], -v[12:13]
	v_cvt_f32_f64_e32 v21, v[20:21]
	v_cos_f32_e32 v20, v21
	v_sin_f32_e32 v21, v21
	v_cvt_f32_i32_e32 v22, s37
	v_mul_f32_e32 v22, v5, v22
	v_cvt_f64_f32_e32 v[22:23], v22
	v_mul_f64 v[12:13], v[22:23], s[42:43]
	v_rndne_f64_e32 v[12:13], v[12:13]
	v_fma_f64 v[22:23], v[22:23], s[42:43], -v[12:13]
	v_cvt_f32_f64_e32 v23, v[22:23]
	v_cos_f32_e32 v22, v23
	v_sin_f32_e32 v23, v23
	v_cvt_f32_i32_e32 v24, s38
	v_mul_f32_e32 v24, v5, v24
	v_cvt_f64_f32_e32 v[24:25], v24
	v_mul_f64 v[12:13], v[24:25], s[42:43]
	v_rndne_f64_e32 v[12:13], v[12:13]
	v_fma_f64 v[24:25], v[24:25], s[42:43], -v[12:13]
	v_cvt_f32_f64_e32 v25, v[24:25]
	v_cos_f32_e32 v24, v25
	v_sin_f32_e32 v25, v25
	v_cvt_f32_i32_e32 v26, s39
	v_mul_f32_e32 v26, v5, v26
	v_cvt_f64_f32_e32 v[26:27], v26
	v_mul_f64 v[12:13], v[26:27], s[42:43]
	v_rndne_f64_e32 v[12:13], v[12:13]
	v_fma_f64 v[26:27], v[26:27], s[42:43], -v[12:13]
	v_cvt_f32_f64_e32 v27, v[26:27]
	v_cos_f32_e32 v26, v27
	v_sin_f32_e32 v27, v27
	v_cvt_f32_i32_e32 v28, s40
	v_mul_f32_e32 v28, v5, v28
	v_cvt_f64_f32_e32 v[28:29], v28
	v_mul_f64 v[12:13], v[28:29], s[42:43]
	v_rndne_f64_e32 v[12:13], v[12:13]
	v_fma_f64 v[28:29], v[28:29], s[42:43], -v[12:13]
	v_cvt_f32_f64_e32 v29, v[28:29]
	v_cos_f32_e32 v28, v29
	v_sin_f32_e32 v29, v29
	v_cvt_f32_i32_e32 v30, s41
	v_mul_f32_e32 v30, v5, v30
	v_cvt_f64_f32_e32 v[30:31], v30
	v_mul_f64 v[12:13], v[30:31], s[42:43]
	v_rndne_f64_e32 v[12:13], v[12:13]
	v_fma_f64 v[30:31], v[30:31], s[42:43], -v[12:13]
	v_cvt_f32_f64_e32 v31, v[30:31]
	v_cos_f32_e32 v30, v31
	v_sin_f32_e32 v31, v31
	s_nop 1
	global_store_dwordx2 v6, v[16:17], s[26:27]
	s_add_u32 s26, s26, 0x100000
	s_addc_u32 s27, s27, 0
	global_store_dwordx2 v6, v[18:19], s[26:27]
	s_add_u32 s26, s26, 0x100000
	s_addc_u32 s27, s27, 0
	global_store_dwordx2 v6, v[20:21], s[26:27]
	s_add_u32 s26, s26, 0x100000
	s_addc_u32 s27, s27, 0
	global_store_dwordx2 v6, v[22:23], s[26:27]
	s_add_u32 s26, s26, 0x100000
	s_addc_u32 s27, s27, 0
	global_store_dwordx2 v6, v[24:25], s[26:27]
	s_add_u32 s26, s26, 0x100000
	s_addc_u32 s27, s27, 0
	global_store_dwordx2 v6, v[26:27], s[26:27]
	s_add_u32 s26, s26, 0x100000
	s_addc_u32 s27, s27, 0
	global_store_dwordx2 v6, v[28:29], s[26:27]
	s_add_u32 s26, s26, 0x100000
	s_addc_u32 s27, s27, 0
	global_store_dwordx2 v6, v[30:31], s[26:27]
	s_mov_b32 exec_lo, 0x55555555
	s_mov_b32 exec_hi, 0x55555555
	s_nop 1
	global_store_dwordx2 v7, v[16:17], s[28:29]
	s_add_u32 s28, s28, 0x80000
	s_addc_u32 s29, s29, 0
	global_store_dwordx2 v7, v[18:19], s[28:29]
	s_add_u32 s28, s28, 0x80000
	s_addc_u32 s29, s29, 0
	global_store_dwordx2 v7, v[20:21], s[28:29]
	s_add_u32 s28, s28, 0x80000
	s_addc_u32 s29, s29, 0
	global_store_dwordx2 v7, v[22:23], s[28:29]
	s_add_u32 s28, s28, 0x80000
	s_addc_u32 s29, s29, 0
	global_store_dwordx2 v7, v[24:25], s[28:29]
	s_add_u32 s28, s28, 0x80000
	s_addc_u32 s29, s29, 0
	global_store_dwordx2 v7, v[26:27], s[28:29]
	s_add_u32 s28, s28, 0x80000
	s_addc_u32 s29, s29, 0
	global_store_dwordx2 v7, v[28:29], s[28:29]
	s_add_u32 s28, s28, 0x80000
	s_addc_u32 s29, s29, 0
	global_store_dwordx2 v7, v[30:31], s[28:29]
	s_mov_b64 exec, -1
	s_nop 1
	v_and_b32_e32 v12, 7, v4
	v_lshrrev_b32_e32 v13, 3, v4
	v_lshlrev_b32_e32 v14, 4, v12
	s_mov_b32 s10, 0x5a000
	v_mul_lo_u32 v15, v13, s10
	v_add_u32_e32 v162, v15, v14
	v_add_u32_e32 v163, 0xb400, v162
	v_add_u32_e32 v164, 0x16800, v162
	v_add_u32_e32 v165, 0x21c00, v162
	v_add_u32_e32 v166, 0x2d000, v162
	v_add_u32_e32 v167, 0x38400, v162
	v_add_u32_e32 v168, 0x43800, v162
	v_add_u32_e32 v169, 0x4ec00, v162
	v_lshlrev_b32_e32 v14, 14, v12
	v_lshl_add_u32 v170, v13, 3, v14
	v_add_u32_e32 v171, 0x1000, v170
	v_add_u32_e32 v172, 0x2000, v170
	v_add_u32_e32 v173, 0x3000, v170
	s_mov_b32 s44, 0x42800000
	s_mov_b32 s45, 0x42800000
	s_lshr_b32 s10, s33, 6
	s_lshl_b32 s11, s2, 3
	s_add_u32 s46, s10, s11
	s_add_u32 s64, s90, 0x4000000
	s_addc_u32 s65, s91, 0
	s_cmpk_ge_u32 s46, 0x680
	s_cbranch_scc1 .Lp0c_four
; #define LAS __attribute__((address_space(3)))
; __device__ __forceinline__ void transpose_item_fp8(const float* W, int N, unsigned char* W8, int pitch, int kofs, int k0, int n_src, int n_dst, float scale, LAS float* scr, int lane) {
;     const int r8 = lane >> 3, c4 = lane & 7;
;     f32x4 v[8];
; #pragma unroll
;     for (int i = 0; i < 8; ++i) v[i] = *(const f32x4*)(W + (size_t)(k0 + r8 + 8 * i) * N + n_src + 4 * c4);
; #pragma unroll
;     for (int i = 0; i < 8; ++i) { LAS float* d = scr + (r8 + 8 * i) * 33 + 4 * c4; d[0] = v[i][0]; d[1] = v[i][1]; d[2] = v[i][2]; d[3] = v[i][3]; }
;     asm volatile("s_waitcnt lgkmcnt(0)" ::: "memory");
;     const int n = lane & 31, cp = lane >> 5;
; #pragma unroll
;     for (int q = 0; q < 2; ++q) { const int ck = (2 * cp + q) * 16; const LAS float* sp = scr + ck * 33 + n; u32x4 o;
; #pragma unroll
;         for (int w = 0; w < 4; ++w) o[w] = pack_fp8x4(sp[(4 * w) * 33] * scale, sp[(4 * w + 1) * 33] * scale, sp[(4 * w + 2) * 33] * scale, sp[(4 * w + 3) * 33] * scale);
;         *(u32x4*)(W8 + (size_t)(n_dst + n) * pitch + kofs + k0 + ck) = o; }
;     asm volatile("s_waitcnt lgkmcnt(0)" ::: "memory");
; }
; __global__ void __launch_bounds__(512, 2) hybrid_fwd(Args a) {
;     ...
;         constexpr int I_IN = (D / 64) * (DIN / 32);
;         for (int it = gw; it < I_IN; it += NGW) { const int nb = it % (DIN / 32), kb = it / (DIN / 32);
;             if ((a.fp8mask >> (nb >> 3)) & 1ull) transpose_item_fp8(a.w_in, DIN, (unsigned char*)WinT, 4096, 0, 64 * kb, gemm_col_to_orig(32 * nb), 32 * nb, W8_SCALE, scr, lane);
	s_add_u32 s47, s46, 0x0
	s_mul_hi_u32 s48, s47, 0xb60b61
	s_mul_i32 s49, s48, 0x168
	s_sub_u32 s49, s47, s49
	s_lshl_b32 s50, s48, 1
	s_lshr_b32 s51, s49, 3
	s_and_b32 s52, s49, 7
	s_and_b32 s53, s52, 3
	s_lshr_b32 s54, s52, 2
	s_lshl_b32 s55, s53, 6
	s_lshl_b32 s56, s54, 5
	s_add_u32 s55, s55, s56
	s_bfe_u32 s56, s52, 0x10001
	s_lshl_b32 s56, s56, 7
	s_and_b32 s57, s52, 1
	s_lshl_b32 s57, s57, 5
	s_add_u32 s56, s56, s57
	s_lshl_b32 s57, s54, 6
	s_add_u32 s56, s56, s57
	s_lshl_b32 s57, s52, 5
	s_sub_u32 s58, s51, 9
	s_cmp_lt_u32 s58, 12
	s_cselect_b32 s57, s56, s57
	s_cmp_lt_u32 s51, 5
	s_cselect_b32 s57, s55, s57
	s_lshl_b32 s58, s51, 8
	s_add_u32 s57, s57, s58
	s_mul_i32 s58, s50, 0x2d0000
	s_lshl_b32 s57, s57, 2
	s_add_u32 s58, s58, s57
	s_add_u32 s60, s22, s58
	s_addc_u32 s61, s23, 0
	s_lshl_b32 s58, s49, 17
	s_lshl_b32 s59, s50, 6
	s_add_u32 s58, s58, s59
	s_add_u32 s74, s64, s58
	s_addc_u32 s75, s65, 0
	global_load_dwordx4 v[64:67], v162, s[60:61] nt
	global_load_dwordx4 v[68:71], v163, s[60:61] nt
	global_load_dwordx4 v[72:75], v164, s[60:61] nt
	global_load_dwordx4 v[76:79], v165, s[60:61] nt
	global_load_dwordx4 v[80:83], v166, s[60:61] nt
	global_load_dwordx4 v[84:87], v167, s[60:61] nt
	global_load_dwordx4 v[88:91], v168, s[60:61] nt
	global_load_dwordx4 v[92:95], v169, s[60:61] nt
	s_add_u32 s47, s46, 0x0
	s_mul_hi_u32 s48, s47, 0xb60b61
	s_mul_i32 s49, s48, 0x168
	s_sub_u32 s49, s47, s49
	s_lshl_b32 s50, s48, 1
	s_or_b32 s50, s50, 1
	s_lshr_b32 s51, s49, 3
	s_and_b32 s52, s49, 7
	s_and_b32 s53, s52, 3
	s_lshr_b32 s54, s52, 2
	s_lshl_b32 s55, s53, 6
	s_lshl_b32 s56, s54, 5
	s_add_u32 s55, s55, s56
	s_bfe_u32 s56, s52, 0x10001
	s_lshl_b32 s56, s56, 7
	s_and_b32 s57, s52, 1
	s_lshl_b32 s57, s57, 5
	s_add_u32 s56, s56, s57
	s_lshl_b32 s57, s54, 6
	s_add_u32 s56, s56, s57
	s_lshl_b32 s57, s52, 5
	s_sub_u32 s58, s51, 9
	s_cmp_lt_u32 s58, 12
	s_cselect_b32 s57, s56, s57
	s_cmp_lt_u32 s51, 5
	s_cselect_b32 s57, s55, s57
	s_lshl_b32 s58, s51, 8
	s_add_u32 s57, s57, s58
	s_mul_i32 s58, s50, 0x2d0000
	s_lshl_b32 s57, s57, 2
	s_add_u32 s58, s58, s57
	s_add_u32 s60, s22, s58
	s_addc_u32 s61, s23, 0
	s_lshl_b32 s58, s49, 17
	s_lshl_b32 s59, s50, 6
	s_add_u32 s58, s58, s59
	s_add_u32 s76, s64, s58
	s_addc_u32 s77, s65, 0
	global_load_dwordx4 v[96:99], v162, s[60:61] nt
	global_load_dwordx4 v[100:103], v163, s[60:61] nt
	global_load_dwordx4 v[104:107], v164, s[60:61] nt
	global_load_dwordx4 v[108:111], v165, s[60:61] nt
	global_load_dwordx4 v[112:115], v166, s[60:61] nt
	global_load_dwordx4 v[116:119], v167, s[60:61] nt
	global_load_dwordx4 v[120:123], v168, s[60:61] nt
	global_load_dwordx4 v[124:127], v169, s[60:61] nt
	s_add_u32 s47, s46, 0x800
	s_mul_hi_u32 s48, s47, 0xb60b61
	s_mul_i32 s49, s48, 0x168
	s_sub_u32 s49, s47, s49
	s_lshl_b32 s50, s48, 1
	s_lshr_b32 s51, s49, 3
	s_and_b32 s52, s49, 7
	s_and_b32 s53, s52, 3
	s_lshr_b32 s54, s52, 2
	s_lshl_b32 s55, s53, 6
	s_lshl_b32 s56, s54, 5
	s_add_u32 s55, s55, s56
	s_bfe_u32 s56, s52, 0x10001
	s_lshl_b32 s56, s56, 7
	s_and_b32 s57, s52, 1
	s_lshl_b32 s57, s57, 5
	s_add_u32 s56, s56, s57
	s_lshl_b32 s57, s54, 6
	s_add_u32 s56, s56, s57
	s_lshl_b32 s57, s52, 5
	s_sub_u32 s58, s51, 9
	s_cmp_lt_u32 s58, 12
	s_cselect_b32 s57, s56, s57
	s_cmp_lt_u32 s51, 5
	s_cselect_b32 s57, s55, s57
	s_lshl_b32 s58, s51, 8
	s_add_u32 s57, s57, s58
	s_mul_i32 s58, s50, 0x2d0000
	s_lshl_b32 s57, s57, 2
	s_add_u32 s58, s58, s57
	s_add_u32 s60, s22, s58
	s_addc_u32 s61, s23, 0
	s_lshl_b32 s58, s49, 17
	s_lshl_b32 s59, s50, 6
	s_add_u32 s58, s58, s59
	s_add_u32 s78, s64, s58
	s_addc_u32 s79, s65, 0
	global_load_dwordx4 v[128:131], v162, s[60:61] nt
	global_load_dwordx4 v[132:135], v163, s[60:61] nt
	global_load_dwordx4 v[136:139], v164, s[60:61] nt
	global_load_dwordx4 v[140:143], v165, s[60:61] nt
	global_load_dwordx4 v[144:147], v166, s[60:61] nt
	global_load_dwordx4 v[148:151], v167, s[60:61] nt
	global_load_dwordx4 v[152:155], v168, s[60:61] nt
	global_load_dwordx4 v[156:159], v169, s[60:61] nt
	s_waitcnt vmcnt(16)
	v_pk_mul_f32 v[64:65], v[64:65], s[44:45]
	v_pk_mul_f32 v[66:67], v[66:67], s[44:45]
	v_pk_mul_f32 v[68:69], v[68:69], s[44:45]
	v_pk_mul_f32 v[70:71], v[70:71], s[44:45]
	v_pk_mul_f32 v[72:73], v[72:73], s[44:45]
	v_pk_mul_f32 v[74:75], v[74:75], s[44:45]
	v_pk_mul_f32 v[76:77], v[76:77], s[44:45]
	v_pk_mul_f32 v[78:79], v[78:79], s[44:45]
	v_pk_mul_f32 v[80:81], v[80:81], s[44:45]
	v_pk_mul_f32 v[82:83], v[82:83], s[44:45]
	v_pk_mul_f32 v[84:85], v[84:85], s[44:45]
	v_pk_mul_f32 v[86:87], v[86:87], s[44:45]
	v_pk_mul_f32 v[88:89], v[88:89], s[44:45]
	v_pk_mul_f32 v[90:91], v[90:91], s[44:45]
	v_pk_mul_f32 v[92:93], v[92:93], s[44:45]
	v_pk_mul_f32 v[94:95], v[94:95], s[44:45]
	v_cvt_pk_fp8_f32 v8, v64, v68
	v_cvt_pk_fp8_f32 v9, v72, v76
	v_cvt_pk_fp8_f32 v10, v80, v84
	v_cvt_pk_fp8_f32 v11, v88, v92
	v_and_b32_e32 v8, 0xffff, v8
	v_and_b32_e32 v10, 0xffff, v10
	v_lshl_or_b32 v176, v9, 16, v8
	v_lshl_or_b32 v177, v11, 16, v10
	global_store_dwordx2 v170, v[176:177], s[74:75]
	v_cvt_pk_fp8_f32 v8, v65, v69
	v_cvt_pk_fp8_f32 v9, v73, v77
	v_cvt_pk_fp8_f32 v10, v81, v85
	v_cvt_pk_fp8_f32 v11, v89, v93
	v_and_b32_e32 v8, 0xffff, v8
	v_and_b32_e32 v10, 0xffff, v10
	v_lshl_or_b32 v178, v9, 16, v8
	v_lshl_or_b32 v179, v11, 16, v10
	global_store_dwordx2 v171, v[178:179], s[74:75]
	v_cvt_pk_fp8_f32 v8, v66, v70
	v_cvt_pk_fp8_f32 v9, v74, v78
	v_cvt_pk_fp8_f32 v10, v82, v86
	v_cvt_pk_fp8_f32 v11, v90, v94
	v_and_b32_e32 v8, 0xffff, v8
	v_and_b32_e32 v10, 0xffff, v10
	v_lshl_or_b32 v180, v9, 16, v8
	v_lshl_or_b32 v181, v11, 16, v10
	global_store_dwordx2 v172, v[180:181], s[74:75]
	v_cvt_pk_fp8_f32 v8, v67, v71
; #define LAS __attribute__((address_space(3)))
; __device__ __forceinline__ void transpose_item_fp8(const float* W, int N, unsigned char* W8, int pitch, int kofs, int k0, int n_src, int n_dst, float scale, LAS float* scr, int lane) {
;     const int r8 = lane >> 3, c4 = lane & 7;
;     f32x4 v[8];
; #pragma unroll
;     for (int i = 0; i < 8; ++i) v[i] = *(const f32x4*)(W + (size_t)(k0 + r8 + 8 * i) * N + n_src + 4 * c4);
; #pragma unroll
;     for (int i = 0; i < 8; ++i) { LAS float* d = scr + (r8 + 8 * i) * 33 + 4 * c4; d[0] = v[i][0]; d[1] = v[i][1]; d[2] = v[i][2]; d[3] = v[i][3]; }
;     asm volatile("s_waitcnt lgkmcnt(0)" ::: "memory");
;     const int n = lane & 31, cp = lane >> 5;
; #pragma unroll
;     for (int q = 0; q < 2; ++q) { const int ck = (2 * cp + q) * 16; const LAS float* sp = scr + ck * 33 + n; u32x4 o;
; #pragma unroll
;         for (int w = 0; w < 4; ++w) o[w] = pack_fp8x4(sp[(4 * w) * 33] * scale, sp[(4 * w + 1) * 33] * scale, sp[(4 * w + 2) * 33] * scale, sp[(4 * w + 3) * 33] * scale);
;         *(u32x4*)(W8 + (size_t)(n_dst + n) * pitch + kofs + k0 + ck) = o; }
;     asm volatile("s_waitcnt lgkmcnt(0)" ::: "memory");
; }
; __global__ void __launch_bounds__(512, 2) hybrid_fwd(Args a) {
;     ...
;         constexpr int I_IN = (D / 64) * (DIN / 32);
;         for (int it = gw; it < I_IN; it += NGW) { const int nb = it % (DIN / 32), kb = it / (DIN / 32);
;             if ((a.fp8mask >> (nb >> 3)) & 1ull) transpose_item_fp8(a.w_in, DIN, (unsigned char*)WinT, 4096, 0, 64 * kb, gemm_col_to_orig(32 * nb), 32 * nb, W8_SCALE, scr, lane);
	v_cvt_pk_fp8_f32 v9, v75, v79
	v_cvt_pk_fp8_f32 v10, v83, v87
	v_cvt_pk_fp8_f32 v11, v91, v95
	v_and_b32_e32 v8, 0xffff, v8
	v_and_b32_e32 v10, 0xffff, v10
	v_lshl_or_b32 v182, v9, 16, v8
	v_lshl_or_b32 v183, v11, 16, v10
	global_store_dwordx2 v173, v[182:183], s[74:75]
	s_add_u32 s47, s46, 0x800
	s_mul_hi_u32 s48, s47, 0xb60b61
	s_mul_i32 s49, s48, 0x168
	s_sub_u32 s49, s47, s49
	s_lshl_b32 s50, s48, 1
	s_or_b32 s50, s50, 1
	s_lshr_b32 s51, s49, 3
	s_and_b32 s52, s49, 7
	s_and_b32 s53, s52, 3
	s_lshr_b32 s54, s52, 2
	s_lshl_b32 s55, s53, 6
	s_lshl_b32 s56, s54, 5
	s_add_u32 s55, s55, s56
	s_bfe_u32 s56, s52, 0x10001
	s_lshl_b32 s56, s56, 7
	s_and_b32 s57, s52, 1
	s_lshl_b32 s57, s57, 5
	s_add_u32 s56, s56, s57
	s_lshl_b32 s57, s54, 6
	s_add_u32 s56, s56, s57
	s_lshl_b32 s57, s52, 5
	s_sub_u32 s58, s51, 9
	s_cmp_lt_u32 s58, 12
	s_cselect_b32 s57, s56, s57
	s_cmp_lt_u32 s51, 5
	s_cselect_b32 s57, s55, s57
	s_lshl_b32 s58, s51, 8
	s_add_u32 s57, s57, s58
	s_mul_i32 s58, s50, 0x2d0000
	s_lshl_b32 s57, s57, 2
	s_add_u32 s58, s58, s57
	s_add_u32 s60, s22, s58
	s_addc_u32 s61, s23, 0
	s_lshl_b32 s58, s49, 17
	s_lshl_b32 s59, s50, 6
	s_add_u32 s58, s58, s59
	s_add_u32 s74, s64, s58
	s_addc_u32 s75, s65, 0
	global_load_dwordx4 v[64:67], v162, s[60:61] nt
	global_load_dwordx4 v[68:71], v163, s[60:61] nt
	global_load_dwordx4 v[72:75], v164, s[60:61] nt
	global_load_dwordx4 v[76:79], v165, s[60:61] nt
	global_load_dwordx4 v[80:83], v166, s[60:61] nt
	global_load_dwordx4 v[84:87], v167, s[60:61] nt
	global_load_dwordx4 v[88:91], v168, s[60:61] nt
	global_load_dwordx4 v[92:95], v169, s[60:61] nt
	s_waitcnt vmcnt(20)
	v_pk_mul_f32 v[96:97], v[96:97], s[44:45]
	v_pk_mul_f32 v[98:99], v[98:99], s[44:45]
	v_pk_mul_f32 v[100:101], v[100:101], s[44:45]
	v_pk_mul_f32 v[102:103], v[102:103], s[44:45]
	v_pk_mul_f32 v[104:105], v[104:105], s[44:45]
	v_pk_mul_f32 v[106:107], v[106:107], s[44:45]
	v_pk_mul_f32 v[108:109], v[108:109], s[44:45]
	v_pk_mul_f32 v[110:111], v[110:111], s[44:45]
	v_pk_mul_f32 v[112:113], v[112:113], s[44:45]
	v_pk_mul_f32 v[114:115], v[114:115], s[44:45]
	v_pk_mul_f32 v[116:117], v[116:117], s[44:45]
	v_pk_mul_f32 v[118:119], v[118:119], s[44:45]
	v_pk_mul_f32 v[120:121], v[120:121], s[44:45]
	v_pk_mul_f32 v[122:123], v[122:123], s[44:45]
	v_pk_mul_f32 v[124:125], v[124:125], s[44:45]
	v_pk_mul_f32 v[126:127], v[126:127], s[44:45]
	v_cvt_pk_fp8_f32 v8, v96, v100
	v_cvt_pk_fp8_f32 v9, v104, v108
	v_cvt_pk_fp8_f32 v10, v112, v116
	v_cvt_pk_fp8_f32 v11, v120, v124
	v_and_b32_e32 v8, 0xffff, v8
	v_and_b32_e32 v10, 0xffff, v10
	v_lshl_or_b32 v184, v9, 16, v8
	v_lshl_or_b32 v185, v11, 16, v10
	global_store_dwordx2 v170, v[184:185], s[76:77]
	v_cvt_pk_fp8_f32 v8, v97, v101
	v_cvt_pk_fp8_f32 v9, v105, v109
	v_cvt_pk_fp8_f32 v10, v113, v117
	v_cvt_pk_fp8_f32 v11, v121, v125
	v_and_b32_e32 v8, 0xffff, v8
	v_and_b32_e32 v10, 0xffff, v10
	v_lshl_or_b32 v186, v9, 16, v8
	v_lshl_or_b32 v187, v11, 16, v10
	global_store_dwordx2 v171, v[186:187], s[76:77]
	v_cvt_pk_fp8_f32 v8, v98, v102
	v_cvt_pk_fp8_f32 v9, v106, v110
	v_cvt_pk_fp8_f32 v10, v114, v118
	v_cvt_pk_fp8_f32 v11, v122, v126
	v_and_b32_e32 v8, 0xffff, v8
	v_and_b32_e32 v10, 0xffff, v10
	v_lshl_or_b32 v188, v9, 16, v8
	v_lshl_or_b32 v189, v11, 16, v10
	global_store_dwordx2 v172, v[188:189], s[76:77]
	v_cvt_pk_fp8_f32 v8, v99, v103
	v_cvt_pk_fp8_f32 v9, v107, v111
	v_cvt_pk_fp8_f32 v10, v115, v119
	v_cvt_pk_fp8_f32 v11, v123, v127
	v_and_b32_e32 v8, 0xffff, v8
	v_and_b32_e32 v10, 0xffff, v10
	v_lshl_or_b32 v190, v9, 16, v8
	v_lshl_or_b32 v191, v11, 16, v10
	global_store_dwordx2 v173, v[190:191], s[76:77]
	s_add_u32 s47, s46, 0x1000
	s_mul_hi_u32 s48, s47, 0xb60b61
	s_mul_i32 s49, s48, 0x168
	s_sub_u32 s49, s47, s49
	s_lshl_b32 s50, s48, 1
	s_lshr_b32 s51, s49, 3
	s_and_b32 s52, s49, 7
	s_and_b32 s53, s52, 3
	s_lshr_b32 s54, s52, 2
	s_lshl_b32 s55, s53, 6
	s_lshl_b32 s56, s54, 5
	s_add_u32 s55, s55, s56
	s_bfe_u32 s56, s52, 0x10001
	s_lshl_b32 s56, s56, 7
	s_and_b32 s57, s52, 1
	s_lshl_b32 s57, s57, 5
	s_add_u32 s56, s56, s57
	s_lshl_b32 s57, s54, 6
	s_add_u32 s56, s56, s57
	s_lshl_b32 s57, s52, 5
	s_sub_u32 s58, s51, 9
	s_cmp_lt_u32 s58, 12
	s_cselect_b32 s57, s56, s57
	s_cmp_lt_u32 s51, 5
	s_cselect_b32 s57, s55, s57
	s_lshl_b32 s58, s51, 8
	s_add_u32 s57, s57, s58
	s_mul_i32 s58, s50, 0x2d0000
	s_lshl_b32 s57, s57, 2
	s_add_u32 s58, s58, s57
	s_add_u32 s60, s22, s58
	s_addc_u32 s61, s23, 0
	s_lshl_b32 s58, s49, 17
	s_lshl_b32 s59, s50, 6
	s_add_u32 s58, s58, s59
	s_add_u32 s76, s64, s58
	s_addc_u32 s77, s65, 0
	global_load_dwordx4 v[96:99], v162, s[60:61] nt
	global_load_dwordx4 v[100:103], v163, s[60:61] nt
	global_load_dwordx4 v[104:107], v164, s[60:61] nt
	global_load_dwordx4 v[108:111], v165, s[60:61] nt
	global_load_dwordx4 v[112:115], v166, s[60:61] nt
	global_load_dwordx4 v[116:119], v167, s[60:61] nt
	global_load_dwordx4 v[120:123], v168, s[60:61] nt
	global_load_dwordx4 v[124:127], v169, s[60:61] nt
	s_waitcnt vmcnt(24)
; #define LAS __attribute__((address_space(3)))
; __device__ __forceinline__ void transpose_item_fp8(const float* W, int N, unsigned char* W8, int pitch, int kofs, int k0, int n_src, int n_dst, float scale, LAS float* scr, int lane) {
;     const int r8 = lane >> 3, c4 = lane & 7;
;     f32x4 v[8];
; #pragma unroll
;     for (int i = 0; i < 8; ++i) v[i] = *(const f32x4*)(W + (size_t)(k0 + r8 + 8 * i) * N + n_src + 4 * c4);
; #pragma unroll
;     for (int i = 0; i < 8; ++i) { LAS float* d = scr + (r8 + 8 * i) * 33 + 4 * c4; d[0] = v[i][0]; d[1] = v[i][1]; d[2] = v[i][2]; d[3] = v[i][3]; }
;     asm volatile("s_waitcnt lgkmcnt(0)" ::: "memory");
;     const int n = lane & 31, cp = lane >> 5;
; #pragma unroll
;     for (int q = 0; q < 2; ++q) { const int ck = (2 * cp + q) * 16; const LAS float* sp = scr + ck * 33 + n; u32x4 o;
; #pragma unroll
;         for (int w = 0; w < 4; ++w) o[w] = pack_fp8x4(sp[(4 * w) * 33] * scale, sp[(4 * w + 1) * 33] * scale, sp[(4 * w + 2) * 33] * scale, sp[(4 * w + 3) * 33] * scale);
;         *(u32x4*)(W8 + (size_t)(n_dst + n) * pitch + kofs + k0 + ck) = o; }
;     asm volatile("s_waitcnt lgkmcnt(0)" ::: "memory");
; }
; __global__ void __launch_bounds__(512, 2) hybrid_fwd(Args a) {
;     ...
;         constexpr int I_IN = (D / 64) * (DIN / 32);
;         for (int it = gw; it < I_IN; it += NGW) { const int nb = it % (DIN / 32), kb = it / (DIN / 32);
;             if ((a.fp8mask >> (nb >> 3)) & 1ull) transpose_item_fp8(a.w_in, DIN, (unsigned char*)WinT, 4096, 0, 64 * kb, gemm_col_to_orig(32 * nb), 32 * nb, W8_SCALE, scr, lane);
	v_pk_mul_f32 v[128:129], v[128:129], s[44:45]
	v_pk_mul_f32 v[130:131], v[130:131], s[44:45]
	v_pk_mul_f32 v[132:133], v[132:133], s[44:45]
	v_pk_mul_f32 v[134:135], v[134:135], s[44:45]
	v_pk_mul_f32 v[136:137], v[136:137], s[44:45]
	v_pk_mul_f32 v[138:139], v[138:139], s[44:45]
	v_pk_mul_f32 v[140:141], v[140:141], s[44:45]
	v_pk_mul_f32 v[142:143], v[142:143], s[44:45]
	v_pk_mul_f32 v[144:145], v[144:145], s[44:45]
	v_pk_mul_f32 v[146:147], v[146:147], s[44:45]
	v_pk_mul_f32 v[148:149], v[148:149], s[44:45]
	v_pk_mul_f32 v[150:151], v[150:151], s[44:45]
	v_pk_mul_f32 v[152:153], v[152:153], s[44:45]
	v_pk_mul_f32 v[154:155], v[154:155], s[44:45]
	v_pk_mul_f32 v[156:157], v[156:157], s[44:45]
	v_pk_mul_f32 v[158:159], v[158:159], s[44:45]
	v_cvt_pk_fp8_f32 v8, v128, v132
	v_cvt_pk_fp8_f32 v9, v136, v140
	v_cvt_pk_fp8_f32 v10, v144, v148
	v_cvt_pk_fp8_f32 v11, v152, v156
	v_and_b32_e32 v8, 0xffff, v8
	v_and_b32_e32 v10, 0xffff, v10
	v_lshl_or_b32 v176, v9, 16, v8
	v_lshl_or_b32 v177, v11, 16, v10
	global_store_dwordx2 v170, v[176:177], s[78:79]
	v_cvt_pk_fp8_f32 v8, v129, v133
	v_cvt_pk_fp8_f32 v9, v137, v141
	v_cvt_pk_fp8_f32 v10, v145, v149
	v_cvt_pk_fp8_f32 v11, v153, v157
	v_and_b32_e32 v8, 0xffff, v8
	v_and_b32_e32 v10, 0xffff, v10
	v_lshl_or_b32 v178, v9, 16, v8
	v_lshl_or_b32 v179, v11, 16, v10
	global_store_dwordx2 v171, v[178:179], s[78:79]
	v_cvt_pk_fp8_f32 v8, v130, v134
	v_cvt_pk_fp8_f32 v9, v138, v142
	v_cvt_pk_fp8_f32 v10, v146, v150
	v_cvt_pk_fp8_f32 v11, v154, v158
	v_and_b32_e32 v8, 0xffff, v8
	v_and_b32_e32 v10, 0xffff, v10
	v_lshl_or_b32 v180, v9, 16, v8
	v_lshl_or_b32 v181, v11, 16, v10
	global_store_dwordx2 v172, v[180:181], s[78:79]
	v_cvt_pk_fp8_f32 v8, v131, v135
	v_cvt_pk_fp8_f32 v9, v139, v143
	v_cvt_pk_fp8_f32 v10, v147, v151
	v_cvt_pk_fp8_f32 v11, v155, v159
	v_and_b32_e32 v8, 0xffff, v8
	v_and_b32_e32 v10, 0xffff, v10
	v_lshl_or_b32 v182, v9, 16, v8
	v_lshl_or_b32 v183, v11, 16, v10
	global_store_dwordx2 v173, v[182:183], s[78:79]
	s_add_u32 s47, s46, 0x1000
	s_mul_hi_u32 s48, s47, 0xb60b61
	s_mul_i32 s49, s48, 0x168
	s_sub_u32 s49, s47, s49
	s_lshl_b32 s50, s48, 1
	s_or_b32 s50, s50, 1
	s_lshr_b32 s51, s49, 3
	s_and_b32 s52, s49, 7
	s_and_b32 s53, s52, 3
	s_lshr_b32 s54, s52, 2
	s_lshl_b32 s55, s53, 6
	s_lshl_b32 s56, s54, 5
	s_add_u32 s55, s55, s56
	s_bfe_u32 s56, s52, 0x10001
	s_lshl_b32 s56, s56, 7
	s_and_b32 s57, s52, 1
	s_lshl_b32 s57, s57, 5
	s_add_u32 s56, s56, s57
	s_lshl_b32 s57, s54, 6
	s_add_u32 s56, s56, s57
	s_lshl_b32 s57, s52, 5
	s_sub_u32 s58, s51, 9
	s_cmp_lt_u32 s58, 12
	s_cselect_b32 s57, s56, s57
	s_cmp_lt_u32 s51, 5
	s_cselect_b32 s57, s55, s57
	s_lshl_b32 s58, s51, 8
	s_add_u32 s57, s57, s58
	s_mul_i32 s58, s50, 0x2d0000
	s_lshl_b32 s57, s57, 2
	s_add_u32 s58, s58, s57
	s_add_u32 s60, s22, s58
	s_addc_u32 s61, s23, 0
	s_lshl_b32 s58, s49, 17
	s_lshl_b32 s59, s50, 6
	s_add_u32 s58, s58, s59
	s_add_u32 s78, s64, s58
	s_addc_u32 s79, s65, 0
	global_load_dwordx4 v[128:131], v162, s[60:61] nt
	global_load_dwordx4 v[132:135], v163, s[60:61] nt
	global_load_dwordx4 v[136:139], v164, s[60:61] nt
	global_load_dwordx4 v[140:143], v165, s[60:61] nt
	global_load_dwordx4 v[144:147], v166, s[60:61] nt
	global_load_dwordx4 v[148:151], v167, s[60:61] nt
	global_load_dwordx4 v[152:155], v168, s[60:61] nt
	global_load_dwordx4 v[156:159], v169, s[60:61] nt
	s_waitcnt vmcnt(24)
	v_pk_mul_f32 v[64:65], v[64:65], s[44:45]
	v_pk_mul_f32 v[66:67], v[66:67], s[44:45]
	v_pk_mul_f32 v[68:69], v[68:69], s[44:45]
	v_pk_mul_f32 v[70:71], v[70:71], s[44:45]
	v_pk_mul_f32 v[72:73], v[72:73], s[44:45]
	v_pk_mul_f32 v[74:75], v[74:75], s[44:45]
	v_pk_mul_f32 v[76:77], v[76:77], s[44:45]
	v_pk_mul_f32 v[78:79], v[78:79], s[44:45]
	v_pk_mul_f32 v[80:81], v[80:81], s[44:45]
	v_pk_mul_f32 v[82:83], v[82:83], s[44:45]
	v_pk_mul_f32 v[84:85], v[84:85], s[44:45]
	v_pk_mul_f32 v[86:87], v[86:87], s[44:45]
	v_pk_mul_f32 v[88:89], v[88:89], s[44:45]
	v_pk_mul_f32 v[90:91], v[90:91], s[44:45]
	v_pk_mul_f32 v[92:93], v[92:93], s[44:45]
	v_pk_mul_f32 v[94:95], v[94:95], s[44:45]
	v_cvt_pk_fp8_f32 v8, v64, v68
	v_cvt_pk_fp8_f32 v9, v72, v76
	v_cvt_pk_fp8_f32 v10, v80, v84
	v_cvt_pk_fp8_f32 v11, v88, v92
	v_and_b32_e32 v8, 0xffff, v8
	v_and_b32_e32 v10, 0xffff, v10
	v_lshl_or_b32 v184, v9, 16, v8
	v_lshl_or_b32 v185, v11, 16, v10
	global_store_dwordx2 v170, v[184:185], s[74:75]
	v_cvt_pk_fp8_f32 v8, v65, v69
	v_cvt_pk_fp8_f32 v9, v73, v77
	v_cvt_pk_fp8_f32 v10, v81, v85
	v_cvt_pk_fp8_f32 v11, v89, v93
	v_and_b32_e32 v8, 0xffff, v8
	v_and_b32_e32 v10, 0xffff, v10
	v_lshl_or_b32 v186, v9, 16, v8
	v_lshl_or_b32 v187, v11, 16, v10
	global_store_dwordx2 v171, v[186:187], s[74:75]
	v_cvt_pk_fp8_f32 v8, v66, v70
	v_cvt_pk_fp8_f32 v9, v74, v78
	v_cvt_pk_fp8_f32 v10, v82, v86
	v_cvt_pk_fp8_f32 v11, v90, v94
	v_and_b32_e32 v8, 0xffff, v8
	v_and_b32_e32 v10, 0xffff, v10
	v_lshl_or_b32 v188, v9, 16, v8
	v_lshl_or_b32 v189, v11, 16, v10
	global_store_dwordx2 v172, v[188:189], s[74:75]
	v_cvt_pk_fp8_f32 v8, v67, v71
	v_cvt_pk_fp8_f32 v9, v75, v79
	v_cvt_pk_fp8_f32 v10, v83, v87
	v_cvt_pk_fp8_f32 v11, v91, v95
	v_and_b32_e32 v8, 0xffff, v8
	v_and_b32_e32 v10, 0xffff, v10
	v_lshl_or_b32 v190, v9, 16, v8
	v_lshl_or_b32 v191, v11, 16, v10
	global_store_dwordx2 v173, v[190:191], s[74:75]
	s_waitcnt vmcnt(16)
; #define LAS __attribute__((address_space(3)))
; __device__ __forceinline__ void transpose_item_fp8(const float* W, int N, unsigned char* W8, int pitch, int kofs, int k0, int n_src, int n_dst, float scale, LAS float* scr, int lane) {
;     const int r8 = lane >> 3, c4 = lane & 7;
;     f32x4 v[8];
; #pragma unroll
;     for (int i = 0; i < 8; ++i) v[i] = *(const f32x4*)(W + (size_t)(k0 + r8 + 8 * i) * N + n_src + 4 * c4);
; #pragma unroll
;     for (int i = 0; i < 8; ++i) { LAS float* d = scr + (r8 + 8 * i) * 33 + 4 * c4; d[0] = v[i][0]; d[1] = v[i][1]; d[2] = v[i][2]; d[3] = v[i][3]; }
;     asm volatile("s_waitcnt lgkmcnt(0)" ::: "memory");
;     const int n = lane & 31, cp = lane >> 5;
; #pragma unroll
;     for (int q = 0; q < 2; ++q) { const int ck = (2 * cp + q) * 16; const LAS float* sp = scr + ck * 33 + n; u32x4 o;
; #pragma unroll
;         for (int w = 0; w < 4; ++w) o[w] = pack_fp8x4(sp[(4 * w) * 33] * scale, sp[(4 * w + 1) * 33] * scale, sp[(4 * w + 2) * 33] * scale, sp[(4 * w + 3) * 33] * scale);
;         *(u32x4*)(W8 + (size_t)(n_dst + n) * pitch + kofs + k0 + ck) = o; }
;     asm volatile("s_waitcnt lgkmcnt(0)" ::: "memory");
; }
	v_pk_mul_f32 v[96:97], v[96:97], s[44:45]
	v_pk_mul_f32 v[98:99], v[98:99], s[44:45]
	v_pk_mul_f32 v[100:101], v[100:101], s[44:45]
	v_pk_mul_f32 v[102:103], v[102:103], s[44:45]
	v_pk_mul_f32 v[104:105], v[104:105], s[44:45]
	v_pk_mul_f32 v[106:107], v[106:107], s[44:45]
	v_pk_mul_f32 v[108:109], v[108:109], s[44:45]
	v_pk_mul_f32 v[110:111], v[110:111], s[44:45]
	v_pk_mul_f32 v[112:113], v[112:113], s[44:45]
	v_pk_mul_f32 v[114:115], v[114:115], s[44:45]
	v_pk_mul_f32 v[116:117], v[116:117], s[44:45]
	v_pk_mul_f32 v[118:119], v[118:119], s[44:45]
	v_pk_mul_f32 v[120:121], v[120:121], s[44:45]
	v_pk_mul_f32 v[122:123], v[122:123], s[44:45]
	v_pk_mul_f32 v[124:125], v[124:125], s[44:45]
	v_pk_mul_f32 v[126:127], v[126:127], s[44:45]
	v_cvt_pk_fp8_f32 v8, v96, v100
	v_cvt_pk_fp8_f32 v9, v104, v108
	v_cvt_pk_fp8_f32 v10, v112, v116
	v_cvt_pk_fp8_f32 v11, v120, v124
	v_and_b32_e32 v8, 0xffff, v8
	v_and_b32_e32 v10, 0xffff, v10
	v_lshl_or_b32 v176, v9, 16, v8
	v_lshl_or_b32 v177, v11, 16, v10
	global_store_dwordx2 v170, v[176:177], s[76:77]
	v_cvt_pk_fp8_f32 v8, v97, v101
	v_cvt_pk_fp8_f32 v9, v105, v109
	v_cvt_pk_fp8_f32 v10, v113, v117
	v_cvt_pk_fp8_f32 v11, v121, v125
	v_and_b32_e32 v8, 0xffff, v8
	v_and_b32_e32 v10, 0xffff, v10
	v_lshl_or_b32 v178, v9, 16, v8
	v_lshl_or_b32 v179, v11, 16, v10
	global_store_dwordx2 v171, v[178:179], s[76:77]
	v_cvt_pk_fp8_f32 v8, v98, v102
	v_cvt_pk_fp8_f32 v9, v106, v110
	v_cvt_pk_fp8_f32 v10, v114, v118
	v_cvt_pk_fp8_f32 v11, v122, v126
	v_and_b32_e32 v8, 0xffff, v8
	v_and_b32_e32 v10, 0xffff, v10
	v_lshl_or_b32 v180, v9, 16, v8
	v_lshl_or_b32 v181, v11, 16, v10
	global_store_dwordx2 v172, v[180:181], s[76:77]
	v_cvt_pk_fp8_f32 v8, v99, v103
	v_cvt_pk_fp8_f32 v9, v107, v111
	v_cvt_pk_fp8_f32 v10, v115, v119
	v_cvt_pk_fp8_f32 v11, v123, v127
	v_and_b32_e32 v8, 0xffff, v8
	v_and_b32_e32 v10, 0xffff, v10
	v_lshl_or_b32 v182, v9, 16, v8
	v_lshl_or_b32 v183, v11, 16, v10
	global_store_dwordx2 v173, v[182:183], s[76:77]
	s_waitcnt vmcnt(8)
	v_pk_mul_f32 v[128:129], v[128:129], s[44:45]
	v_pk_mul_f32 v[130:131], v[130:131], s[44:45]
	v_pk_mul_f32 v[132:133], v[132:133], s[44:45]
	v_pk_mul_f32 v[134:135], v[134:135], s[44:45]
	v_pk_mul_f32 v[136:137], v[136:137], s[44:45]
	v_pk_mul_f32 v[138:139], v[138:139], s[44:45]
	v_pk_mul_f32 v[140:141], v[140:141], s[44:45]
	v_pk_mul_f32 v[142:143], v[142:143], s[44:45]
	v_pk_mul_f32 v[144:145], v[144:145], s[44:45]
	v_pk_mul_f32 v[146:147], v[146:147], s[44:45]
	v_pk_mul_f32 v[148:149], v[148:149], s[44:45]
	v_pk_mul_f32 v[150:151], v[150:151], s[44:45]
	v_pk_mul_f32 v[152:153], v[152:153], s[44:45]
	v_pk_mul_f32 v[154:155], v[154:155], s[44:45]
	v_pk_mul_f32 v[156:157], v[156:157], s[44:45]
	v_pk_mul_f32 v[158:159], v[158:159], s[44:45]
	v_cvt_pk_fp8_f32 v8, v128, v132
	v_cvt_pk_fp8_f32 v9, v136, v140
	v_cvt_pk_fp8_f32 v10, v144, v148
	v_cvt_pk_fp8_f32 v11, v152, v156
	v_and_b32_e32 v8, 0xffff, v8
	v_and_b32_e32 v10, 0xffff, v10
	v_lshl_or_b32 v184, v9, 16, v8
	v_lshl_or_b32 v185, v11, 16, v10
	global_store_dwordx2 v170, v[184:185], s[78:79]
	v_cvt_pk_fp8_f32 v8, v129, v133
	v_cvt_pk_fp8_f32 v9, v137, v141
	v_cvt_pk_fp8_f32 v10, v145, v149
	v_cvt_pk_fp8_f32 v11, v153, v157
	v_and_b32_e32 v8, 0xffff, v8
	v_and_b32_e32 v10, 0xffff, v10
	v_lshl_or_b32 v186, v9, 16, v8
	v_lshl_or_b32 v187, v11, 16, v10
	global_store_dwordx2 v171, v[186:187], s[78:79]
	v_cvt_pk_fp8_f32 v8, v130, v134
	v_cvt_pk_fp8_f32 v9, v138, v142
	v_cvt_pk_fp8_f32 v10, v146, v150
	v_cvt_pk_fp8_f32 v11, v154, v158
	v_and_b32_e32 v8, 0xffff, v8
	v_and_b32_e32 v10, 0xffff, v10
	v_lshl_or_b32 v188, v9, 16, v8
	v_lshl_or_b32 v189, v11, 16, v10
	global_store_dwordx2 v172, v[188:189], s[78:79]
	v_cvt_pk_fp8_f32 v8, v131, v135
	v_cvt_pk_fp8_f32 v9, v139, v143
	v_cvt_pk_fp8_f32 v10, v147, v151
	v_cvt_pk_fp8_f32 v11, v155, v159
	v_and_b32_e32 v8, 0xffff, v8
	v_and_b32_e32 v10, 0xffff, v10
	v_lshl_or_b32 v190, v9, 16, v8
	v_lshl_or_b32 v191, v11, 16, v10
	global_store_dwordx2 v173, v[190:191], s[78:79]
	s_branch .Lp0c_end

; __device__ __forceinline__ unsigned cvt_pk_bf16(float lo, float hi) { unsigned r; asm volatile("v_cvt_pk_bf16_f32 %0, %1, %2" : "=v"(r) : "v"(lo), "v"(hi)); return r; }
; __global__ void __launch_bounds__(512, 2) hybrid_fwd(Args a) {
;     ...
;         const size_t gt = (size_t)bx * 512 + tid, GT = (size_t)G * 512;
;         {
;             const size_t NCH = (size_t)M * D / 8;
;             for (size_t i0 = gt; i0 < NCH; i0 += 4 * GT) {
;                 f32x4 v[4][2];
; #pragma unroll
;                 for (int u = 0; u < 4; ++u) { const size_t i = i0 + (size_t)u * GT; if (i < NCH) { v[u][0] = ((const f32x4*)a.x)[2 * i]; v[u][1] = ((const f32x4*)a.x)[2 * i + 1]; } }
; #pragma unroll
;                 for (int u = 0; u < 4; ++u) { const size_t i = i0 + (size_t)u * GT; if (i < NCH) {
;                     u32x4 w; w.x = cvt_pk_bf16(v[u][0][0], v[u][0][1]); w.y = cvt_pk_bf16(v[u][0][2], v[u][0][3]); w.z = cvt_pk_bf16(v[u][1][0], v[u][1][1]); w.w = cvt_pk_bf16(v[u][1][2], v[u][1][3]);
;                     if (a.n_bf16 > 0) ((u32x4*)XB)[i] = w;
;                     const unsigned p0 = pack_fp8x4(v[u][0][0], v[u][0][1], v[u][0][2], v[u][0][3]), p1 = pack_fp8x4(v[u][1][0], v[u][1][1], v[u][1][2], v[u][1][3]);
;                     ((u32x2*)XB8)[i] = (u32x2){p0, p1}; } }
.Lp0_done:
	s_cmp_eq_u32 s100, 1
	s_cselect_b64 vcc, 0, vcc
	s_and_saveexec_b64 s[16:17], vcc
	s_cbranch_execz .LBB0_25
	s_load_dword s6, s[70:71], 0x1c0
	s_load_dwordx2 s[18:19], s[70:71], 0x0
	v_lshlrev_b32_e32 v2, 4, v160
	v_mov_b32_e32 v3, v161
	v_mov_b32_e32 v41, v161
	s_waitcnt lgkmcnt(0)
	s_cmp_gt_i32 s6, 0
	s_cselect_b64 s[20:21], -1, 0
	s_lshl_b64 s[6:7], s[2:3], 13
	v_lshl_add_u64 v[42:43], s[6:7], 0, v[2:3]
	s_lshl_b64 s[22:23], s[92:93], 15
	s_lshl_b64 s[6:7], s[2:3], 12
	s_lshl_b64 s[8:9], s[92:93], 12
	s_add_u32 s8, s6, s8
	s_addc_u32 s9, s7, s9
	s_lshl_b64 s[24:25], s[92:93], 14
	v_lshl_add_u64 v[46:47], s[6:7], 0, v[40:41]
	s_lshl_b64 s[26:27], s[92:93], 11
	s_lshl_b64 s[6:7], s[2:3], 14
	v_lshlrev_b32_e32 v2, 5, v160
	s_lshl_b64 s[28:29], s[92:93], 16
	s_lshl_b64 s[30:31], s[92:93], 10
	v_lshl_add_u64 v[48:49], s[6:7], 0, v[2:3]
	s_add_u32 s6, s4, s14
	s_addc_u32 s7, s5, s15
	v_lshl_add_u64 v[2:3], s[6:7], 0, v[160:161]
	s_add_u32 s6, s30, s4
	s_addc_u32 s7, s31, s5
	s_mul_i32 s34, s92, 0x600
	s_mul_hi_i32 s35, s92, 0x600
	s_add_u32 s4, s34, s4
	s_addc_u32 s5, s35, s5
	v_lshlrev_b64 v[50:51], 5, v[2:3]
	v_lshl_add_u64 v[4:5], s[6:7], 0, v[160:161]
	v_lshlrev_b64 v[58:59], 4, v[2:3]
	v_lshl_add_u64 v[2:3], s[4:5], 0, v[160:161]
	v_lshlrev_b64 v[52:53], 5, v[4:5]
	v_lshlrev_b64 v[60:61], 5, v[2:3]
	v_lshl_add_u64 v[44:45], s[8:9], 0, v[40:41]
	v_or_b32_e32 v52, 16, v52
	v_lshlrev_b64 v[54:55], 3, v[4:5]
	v_lshlrev_b64 v[56:57], 4, v[4:5]
	v_or_b32_e32 v60, 16, v60
	v_lshlrev_b64 v[62:63], 3, v[2:3]
	v_lshlrev_b64 v[64:65], 4, v[2:3]
	s_mov_b64 s[36:37], 0
	s_mov_b64 s[38:39], 0x3fffff
	v_mov_b64_e32 v[66:67], v[38:39]
	s_add_u32 s40, s90, 0x2000000
	s_addc_u32 s41, s91, 0
	s_mov_b64 s[42:43], s[90:91]
	s_branch .LBB0_6

; #define PG8_STAGE(bufoff, gbase, voff) do { _Pragma("unroll") for (int _i = 0; _i < 2; ++_i) \
;         __builtin_amdgcn_global_load_lds((const unsigned*)((const char*)(gbase) + (voff)[_i]), (LAS unsigned*)(lds + (bufoff) + ldsw + _i * 8192), 16, 0, 0); } while (0)
; #define PG8_WAIT_V(n) asm volatile("s_waitcnt vmcnt(" #n ")" ::: "memory")
; #define PG8_BAR __builtin_amdgcn_s_barrier()
; template <class Epi, class Sched, bool FP8 = false>
; __device__ __forceinline__ void gemm_phase(LAS unsigned char* lds, const Gemm g, const Sched& S, const Epi& E) {
;     ...
;     const char* cA = (const char*)g.A + (size_t)cur.pm * tstepA + (size_t)cur.k0 * 2; const char* cB = (const char*)g.Bt + (size_t)cur.pn * tstepB + (size_t)cur.k0 * 2;
;     PG8_STAGE(PG8_SB(0, 0), cB, voffB); PG8_STAGE(PG8_SB(0, 1), cB + hstepB, voffB); PG8_STAGE(PG8_SA(0, 0), cA, voffA); PG8_STAGE(PG8_SA(0, 1), cA + hstepA, voffA);
;     if (wr == 1) PG8_BAR;
;     PG8_WAIT_V(2); PG8_BAR;
;     PG8_STAGE(PG8_SB(1, 0), cB + kstep, voffB); PG8_STAGE(PG8_SA(1, 0), cA + kstep, voffA); PG8_STAGE(PG8_SB(1, 1), cB + hstepB + kstep, voffB);
;     PG8_WAIT_V(6); PG8_BAR;
.LBB0_65:
	s_andn2_b64 vcc, exec, s[4:5]
	s_cbranch_vccnz .LBB0_267
	v_lshrrev_b32_e32 v2, 1, v160
	v_and_b32_e32 v164, 24, v2
	v_lshrrev_b32_e32 v2, 5, v160
	v_and_b32_e32 v2, 4, v2
	v_bfe_u32 v3, v160, 2, 2
	v_lshlrev_b32_e32 v0, 4, v160
	v_bfe_u32 v10, v160, 2, 4
	v_or3_b32 v2, v2, v3, v164
	v_lshrrev_b32_e32 v3, 3, v160
	s_movk_i32 s1, 0x70
	v_bitop3_b32 v8, v0, v162, 48 bitop3:0x6c
	v_and_b32_e32 v9, 64, v160
	v_and_or_b32 v4, v3, s1, v10
	s_movk_i32 s1, 0x60
	v_add_u32_e32 v11, 0x2000, v0
	v_or_b32_e32 v1, v8, v9
	v_and_or_b32 v3, v3, s1, v2
	v_lshrrev_b32_e32 v0, 7, v11
	s_movk_i32 s1, 0xf0
	v_lshl_or_b32 v168, v3, 12, v1
	v_and_or_b32 v3, v0, s1, v10
	s_movk_i32 s1, 0xe0
	s_lshr_b32 s4, s24, 6
	v_and_or_b32 v0, v0, s1, v2
	s_ashr_i32 s9, s8, 31
	s_ashr_i32 s1, s0, 31
	s_lshr_b32 s5, s24, 8
	s_lshl_b32 s47, s4, 10
	s_lshl_b64 s[6:7], s[8:9], 19
	s_lshl_b64 s[10:11], s[0:1], 20
	s_add_u32 s10, s14, s10
	s_addc_u32 s11, s15, s11
	s_add_i32 s48, s47, 0
	s_add_i32 m0, s48, 0x10000
	v_lshl_or_b32 v172, v0, 12, v1
	global_load_lds_dwordx4 v168, s[10:11]
	s_add_i32 m0, s48, 0x12000
	s_add_u32 s18, s10, 0x80000
	global_load_lds_dwordx4 v172, s[10:11]
	s_addc_u32 s19, s11, 0
	s_add_i32 m0, s48, 0x14000
	v_lshl_or_b32 v166, v4, 11, v1
	global_load_lds_dwordx4 v168, s[18:19]
	s_add_i32 m0, s48, 0x16000
	s_add_u32 s6, s90, s6
	s_addc_u32 s7, s91, s7
	s_add_u32 s6, s6, 0x2000000
	s_addc_u32 s7, s7, 0
	s_add_i32 s49, s48, 0x2000
	global_load_lds_dwordx4 v172, s[18:19]
	s_mov_b32 m0, s48
	s_add_u32 s18, s6, 0x40000
	v_lshl_or_b32 v170, v3, 11, v1
	global_load_lds_dwordx4 v166, s[6:7]
	s_mov_b32 m0, s49
	s_addc_u32 s19, s7, 0
	s_add_i32 s50, s48, 0x4000
	global_load_lds_dwordx4 v170, s[6:7]
	s_mov_b32 m0, s50
	s_add_i32 s51, s48, 0x6000
	global_load_lds_dwordx4 v166, s[18:19]
	s_mov_b32 m0, s51
	v_mov_b32_e32 v175, 0
	global_load_lds_dwordx4 v170, s[18:19]
	s_load_dwordx2 s[18:19], s[70:71], 0x18
	v_mov_b32_e32 v169, v175
	v_mov_b32_e32 v173, v175
	v_mov_b32_e32 v167, v175
	v_mov_b32_e32 v171, v175
	s_cmp_eq_u32 s5, 1
	s_mov_b32 s17, 0
	v_lshl_add_u64 v[6:7], s[10:11], 0, v[168:169]
	v_lshl_add_u64 v[4:5], s[10:11], 0, v[172:173]
	v_lshl_add_u64 v[0:1], s[6:7], 0, v[166:167]
	s_cselect_b64 s[20:21], -1, 0
	s_cmp_lg_u32 s5, 1
	v_lshl_add_u64 v[2:3], s[6:7], 0, v[170:171]
	s_cbranch_scc1 .LBB0_68
	s_barrier

; template <class Epi, class Sched, bool FP8 = false>
; __device__ __forceinline__ void gemm_phase(LAS unsigned char* lds, const Gemm g, const Sched& S, const Epi& E) {
;     ...
;         const bool has_next = S.next(ui + 1, nxt);
;         const char* nA = has_next ? (const char*)g.A + (size_t)nxt.pm * tstepA + (size_t)nxt.k0 * 2 : cA; const char* nB = has_next ? (const char*)g.Bt + (size_t)nxt.pn * tstepB + (size_t)nxt.k0 * 2 : cB;
;         const int nt = cur.nt;
;         for (int t = 0; t < nt; t += 2) {
;             const bool last = (t == nt - 2);
;             const char* a1 = cA + (size_t)(t + 1) * kstep;
;             const char* a2 = last ? nA : cA + (size_t)(t + 2) * kstep; const char* b2 = last ? nB : cB + (size_t)(t + 2) * kstep;
;             const char* a3 = a2 + kstep; const char* b3 = b2 + kstep;
;             PG8_LDB(B0, 0, 0); PG8_LDB(B1, 0, 1); PG8_SCHED; PG8_LDA(At, 0, 0); PG8_STAGE(PG8_SA(1, 1), a1 + hstepA, voffA);
;             PG8_WAIT_V(8); PG8_WAIT_L(0); PG8_BAR; PG8_MMA(0, 0, At, B0); PG8_MMA(0, 1, At, B1); PG8_BAR; PG8_SCHED;
;             PG8_LDA(At, 0, 1); PG8_STAGE(PG8_SB(0, 0), b2, voffB); PG8_STAGE(PG8_SB(0, 1), b2 + hstepB, voffB); PG8_STAGE(PG8_SA(0, 0), a2, voffA);
;             PG8_WAIT_V(8); PG8_WAIT_L(0); PG8_BAR; PG8_MMA(1, 0, At, B0); PG8_MMA(1, 1, At, B1); PG8_BAR; PG8_SCHED;
;             PG8_LDB(B0, 1, 0); PG8_LDB(B1, 1, 1); PG8_SCHED; PG8_LDA(At, 1, 0); PG8_STAGE(PG8_SA(0, 1), a2 + hstepA, voffA);
;             PG8_WAIT_V(8); PG8_WAIT_L(0); PG8_BAR; PG8_MMA(0, 0, At, B0); PG8_MMA(0, 1, At, B1); PG8_BAR; PG8_SCHED;
;             PG8_LDA(At, 1, 1); PG8_STAGE(PG8_SB(1, 0), b3, voffB); PG8_STAGE(PG8_SB(1, 1), b3 + hstepB, voffB); PG8_STAGE(PG8_SA(1, 0), a3, voffA);
;             PG8_WAIT_V(8); PG8_WAIT_L(0); PG8_BAR; PG8_MMA(1, 0, At, B0); PG8_MMA(1, 1, At, B1); PG8_BAR; PG8_SCHED;
;         }
;         if (wr == 0) PG8_BAR;
;         if constexpr (FP8) asm volatile("s_nop 15\n\ts_nop 15" ::: "memory");
;         E(acc, cur, wr, wc, fr, fq);
;         if (!has_next) break;
;         if (!E.keep(cur)) {
; #pragma unroll
;             for (int a = 0; a < 2; ++a)
; #pragma unroll
;                 for (int b = 0; b < 2; ++b)
; #pragma unroll
;                     for (int m = 0; m < 4; ++m)
; #pragma unroll
;                         for (int n = 0; n < 2; ++n) acc[a][b][m][n] = (f32x4){0.f, 0.f, 0.f, 0.f};
.LBB0_73:
	s_ashr_i32 s35, s34, 31
	s_lshl_b64 s[38:39], s[34:35], 19
	s_add_u32 s38, s90, s38
	s_addc_u32 s39, s91, s39
	s_add_u32 s38, s38, 0x2000000
	s_addc_u32 s39, s39, 0
	s_and_b64 s[40:41], s[4:5], exec
	s_cselect_b32 s1, s39, s7
	s_cselect_b32 s9, s38, s6
	s_ashr_i32 s37, s36, 31
	s_lshl_b64 s[40:41], s[36:37], 20
	s_add_u32 s40, s14, s40
	s_addc_u32 s41, s15, s41
	s_and_b64 s[42:43], s[4:5], exec
	s_cselect_b32 s16, s41, s11
	s_cselect_b32 s33, s40, s10
	s_add_u32 s6, s6, 0x40080
	s_addc_u32 s7, s7, 0
	s_add_u32 s35, s10, 0x100
	v_mov_b32_e32 v32, 0
	s_addc_u32 s37, s11, 0
	s_mov_b32 s44, -2
	v_mov_b32_e32 v33, v32
	v_mov_b32_e32 v34, v32
	v_mov_b32_e32 v35, v32
	v_mov_b32_e32 v36, v32
	v_mov_b32_e32 v37, v32
	v_mov_b32_e32 v38, v32
	v_mov_b32_e32 v39, v32
	v_mov_b32_e32 v48, v32
	v_mov_b32_e32 v49, v32
	v_mov_b32_e32 v50, v32
	v_mov_b32_e32 v51, v32
	v_mov_b32_e32 v52, v32
	v_mov_b32_e32 v53, v32
	v_mov_b32_e32 v54, v32
	v_mov_b32_e32 v55, v32
	v_mov_b32_e32 v64, v32
	v_mov_b32_e32 v65, v32
	v_mov_b32_e32 v66, v32
	v_mov_b32_e32 v67, v32
	v_mov_b32_e32 v68, v32
	v_mov_b32_e32 v69, v32
	v_mov_b32_e32 v70, v32
	v_mov_b32_e32 v71, v32
	v_mov_b32_e32 v80, v32
	v_mov_b32_e32 v81, v32
	v_mov_b32_e32 v82, v32
	v_mov_b32_e32 v83, v32
	v_mov_b32_e32 v84, v32
	v_mov_b32_e32 v85, v32
	v_mov_b32_e32 v86, v32
	v_mov_b32_e32 v87, v32
	v_mov_b32_e32 v40, v32
	v_mov_b32_e32 v41, v32
	v_mov_b32_e32 v42, v32
	v_mov_b32_e32 v43, v32
	v_mov_b32_e32 v44, v32
	v_mov_b32_e32 v45, v32
	v_mov_b32_e32 v46, v32
	v_mov_b32_e32 v47, v32
	v_mov_b32_e32 v56, v32
	v_mov_b32_e32 v57, v32
	v_mov_b32_e32 v58, v32
	v_mov_b32_e32 v59, v32
	v_mov_b32_e32 v60, v32
	v_mov_b32_e32 v61, v32
	v_mov_b32_e32 v62, v32
	v_mov_b32_e32 v63, v32
	v_mov_b32_e32 v72, v32
	v_mov_b32_e32 v73, v32
	v_mov_b32_e32 v74, v32
	v_mov_b32_e32 v75, v32
	v_mov_b32_e32 v76, v32
	v_mov_b32_e32 v77, v32
	v_mov_b32_e32 v78, v32
	v_mov_b32_e32 v79, v32
	v_mov_b32_e32 v88, v32
	v_mov_b32_e32 v89, v32
	v_mov_b32_e32 v90, v32
	v_mov_b32_e32 v91, v32
	v_mov_b32_e32 v92, v32
	v_mov_b32_e32 v93, v32
	v_mov_b32_e32 v94, v32
	v_mov_b32_e32 v95, v32
	v_mov_b32_e32 v96, v32
	v_mov_b32_e32 v97, v32
	v_mov_b32_e32 v98, v32
	v_mov_b32_e32 v99, v32
	v_mov_b32_e32 v100, v32
	v_mov_b32_e32 v101, v32
	v_mov_b32_e32 v102, v32
	v_mov_b32_e32 v103, v32
	v_mov_b32_e32 v112, v32
	v_mov_b32_e32 v113, v32
	v_mov_b32_e32 v114, v32
	v_mov_b32_e32 v115, v32
	v_mov_b32_e32 v116, v32
	v_mov_b32_e32 v117, v32
	v_mov_b32_e32 v118, v32
	v_mov_b32_e32 v119, v32
	v_mov_b32_e32 v128, v32
	v_mov_b32_e32 v129, v32
	v_mov_b32_e32 v130, v32
	v_mov_b32_e32 v131, v32
	v_mov_b32_e32 v132, v32
	v_mov_b32_e32 v133, v32
	v_mov_b32_e32 v134, v32
	v_mov_b32_e32 v135, v32
	v_mov_b32_e32 v144, v32
	v_mov_b32_e32 v145, v32
	v_mov_b32_e32 v146, v32
	v_mov_b32_e32 v147, v32
	v_mov_b32_e32 v152, v32
	v_mov_b32_e32 v153, v32
	v_mov_b32_e32 v154, v32
	v_mov_b32_e32 v155, v32
	v_mov_b32_e32 v104, v32
	v_mov_b32_e32 v105, v32
	v_mov_b32_e32 v106, v32
	v_mov_b32_e32 v107, v32
	v_mov_b32_e32 v108, v32
	v_mov_b32_e32 v109, v32
	v_mov_b32_e32 v110, v32
	v_mov_b32_e32 v111, v32
	v_mov_b32_e32 v120, v32
	v_mov_b32_e32 v121, v32
	v_mov_b32_e32 v122, v32
	v_mov_b32_e32 v123, v32
	v_mov_b32_e32 v124, v32
	v_mov_b32_e32 v125, v32
	v_mov_b32_e32 v126, v32
	v_mov_b32_e32 v127, v32
	v_mov_b32_e32 v136, v32
	v_mov_b32_e32 v137, v32
	v_mov_b32_e32 v138, v32
	v_mov_b32_e32 v139, v32
	v_mov_b32_e32 v140, v32
	v_mov_b32_e32 v141, v32
	v_mov_b32_e32 v142, v32
	v_mov_b32_e32 v143, v32
	v_mov_b32_e32 v148, v32
	v_mov_b32_e32 v149, v32
	v_mov_b32_e32 v150, v32
	v_mov_b32_e32 v151, v32
	v_mov_b32_e32 v156, v32
	v_mov_b32_e32 v157, v32
	v_mov_b32_e32 v158, v32
	v_mov_b32_e32 v159, v32

;     __device__ __forceinline__ void operator()(f32x4 (&acc)[2][2][4][2], const pg8::Unit& u, int wr, int wc, int fr, int fq) const {
;         typedef _Float16 h8 __attribute__((ext_vector_type(8)));
;         const int row0 = u.pm * 256 + wr * 64 + fr, col0 = u.pn * 256 + wc * 32 + 8 * fq;
; #pragma unroll
;         for (int ai = 0; ai < 2; ++ai)
; #pragma unroll
;             for (int m = 0; m < 4; ++m) {
;                 const int row = row0 + ai * 128 + m * 16; const size_t off = (size_t)row * D + col0;
;                 float s = 0.f, q = 0.f;
; #pragma unroll
;                 for (int bj = 0; bj < 2; ++bj) {
;                     const f32x4 x0 = *(const f32x4*)(x + off + bj * 128), x1 = *(const f32x4*)(x + off + bj * 128 + 4);
;                     const f32x4 z0 = x0 * DN_ALPHA + acc[ai][bj][m][0] * ascale, z1 = x1 * DN_ALPHA + acc[ai][bj][m][1] * ascale;
;                     *(h8*)(z16 + off + bj * 128) = (h8){(_Float16)z0[0], (_Float16)z0[1], (_Float16)z0[2], (_Float16)z0[3], (_Float16)z1[0], (_Float16)z1[1], (_Float16)z1[2], (_Float16)z1[3]};
;                     s += ((z0[0] + z0[1]) + (z0[2] + z0[3])) + ((z1[0] + z1[1]) + (z1[2] + z1[3]));
;                     q += ((z0[0] * z0[0] + z0[1] * z0[1]) + (z0[2] * z0[2] + z0[3] * z0[3])) + ((z1[0] * z1[0] + z1[1] * z1[1]) + (z1[2] * z1[2] + z1[3] * z1[3]));
;                 }
;                 s += __shfl_xor(s, 16); s += __shfl_xor(s, 32); q += __shfl_xor(q, 16); q += __shfl_xor(q, 32);
;                 if (fq == 0) stats[(size_t)row * 32 + u.pn * 4 + wc] = (f32x2){s, q};
;                 asm volatile("" ::: "memory");
;             }
;     }
.LBB0_479:
	v_lshl_add_u32 v2, s12, 8, v188
	v_lshl_or_b32 v0, s6, 8, v189
	v_ashrrev_i32_e32 v3, 31, v2
	v_ashrrev_i32_e32 v1, 31, v0
	v_lshlrev_b64 v[4:5], 11, v[2:3]
	v_lshl_add_u64 v[12:13], v[4:5], 0, v[0:1]
	s_nop 15
	s_nop 15
	v_lshl_add_u64 v[14:15], v[12:13], 2, s[4:5]
	global_load_dwordx4 v[4:7], v[14:15], off nt
	global_load_dwordx4 v[8:11], v[14:15], off offset:16 nt
	v_lshl_add_u64 v[16:17], v[12:13], 1, s[96:97]
	v_xor_b32_e32 v178, 32, v195
	s_waitcnt vmcnt(0)
	v_pk_mul_f32 v[6:7], v[6:7], s[20:21] op_sel_hi:[1,0]
	v_pk_mul_f32 v[4:5], v[4:5], s[20:21] op_sel_hi:[1,0]
	v_pk_mul_f32 v[10:11], v[10:11], s[20:21] op_sel_hi:[1,0]
	v_pk_mul_f32 v[8:9], v[8:9], s[20:21] op_sel_hi:[1,0]
	v_pk_fma_f32 v[18:19], v[158:159], s[22:23], v[6:7] op_sel_hi:[1,0,1]
	v_pk_fma_f32 v[20:21], v[156:157], s[22:23], v[4:5] op_sel_hi:[1,0,1]
	v_pk_fma_f32 v[22:23], v[154:155], s[22:23], v[10:11] op_sel_hi:[1,0,1]
	v_pk_fma_f32 v[8:9], v[152:153], s[22:23], v[8:9] op_sel_hi:[1,0,1]
	v_cvt_pk_f16_f32 v7, v22, v23
	v_cvt_pk_f16_f32 v5, v18, v19
	v_cvt_pk_f16_f32 v6, v8, v9
	v_cvt_pk_f16_f32 v4, v20, v21
	global_store_dwordx4 v[16:17], v[4:7], off
	global_load_dwordx4 v[4:7], v[14:15], off offset:512 nt
	s_nop 0
	global_load_dwordx4 v[12:15], v[14:15], off offset:528 nt
	v_and_b32_e32 v11, 64, v195
	v_add_f32_e32 v24, v20, v21
	v_add_f32_e32 v26, v18, v19
	v_add_f32_e32 v28, v8, v9
	v_add_f32_e32 v30, v22, v23
	v_mul_f32_e32 v153, v20, v20
	v_mul_f32_e32 v21, v21, v21
	v_mul_f32_e32 v155, v18, v18
	v_mul_f32_e32 v19, v19, v19
	v_mul_f32_e32 v157, v8, v8
	v_mul_f32_e32 v9, v9, v9
	v_mul_f32_e32 v159, v22, v22
	v_mul_f32_e32 v23, v23, v23
	v_xor_b32_e32 v10, 16, v195
	v_add_u32_e32 v11, 64, v11
	v_cmp_lt_i32_e32 vcc, v10, v11
	s_waitcnt vmcnt(1)
	v_pk_mul_f32 v[4:5], v[4:5], s[20:21] op_sel_hi:[1,0]
	s_waitcnt vmcnt(0)
	v_pk_mul_f32 v[14:15], v[14:15], s[20:21] op_sel_hi:[1,0]
	v_pk_mul_f32 v[12:13], v[12:13], s[20:21] op_sel_hi:[1,0]
	v_pk_mul_f32 v[6:7], v[6:7], s[20:21] op_sel_hi:[1,0]
	v_pk_fma_f32 v[148:149], v[148:149], s[22:23], v[4:5] op_sel_hi:[1,0,1]
	v_pk_fma_f32 v[4:5], v[146:147], s[22:23], v[14:15] op_sel_hi:[1,0,1]
	v_pk_fma_f32 v[144:145], v[144:145], s[22:23], v[12:13] op_sel_hi:[1,0,1]
	v_pk_fma_f32 v[150:151], v[150:151], s[22:23], v[6:7] op_sel_hi:[1,0,1]
	v_pk_mul_f32 v[6:7], v[4:5], v[4:5]
	v_pk_mul_f32 v[12:13], v[144:145], v[144:145]
	v_mul_f32_e32 v25, v148, v148
	v_pk_mov_b32 v[14:15], v[12:13], v[6:7] op_sel:[1,0]
	v_mov_b32_e32 v13, v7
	v_mul_f32_e32 v27, v149, v149
	v_mul_f32_e32 v29, v150, v150
	v_mul_f32_e32 v31, v151, v151
	v_mov_b32_e32 v152, v148
	v_mov_b32_e32 v20, v149
	v_mov_b32_e32 v154, v150
	v_mov_b32_e32 v18, v151
	v_mov_b32_e32 v156, v144
	v_mov_b32_e32 v8, v145
	v_mov_b32_e32 v158, v4
	v_mov_b32_e32 v22, v5
	v_pk_add_f32 v[12:13], v[14:15], v[12:13]
	v_pk_add_f32 v[6:7], v[152:153], v[20:21]
	v_pk_add_f32 v[18:19], v[154:155], v[18:19]
	v_pk_add_f32 v[8:9], v[156:157], v[8:9]
	v_pk_add_f32 v[20:21], v[158:159], v[22:23]
	v_pk_add_f32 v[22:23], v[24:25], v[26:27]
	v_pk_add_f32 v[24:25], v[28:29], v[30:31]
	v_pk_add_f32 v[12:13], v[12:13], v[12:13] op_sel_hi:[0,1]
	v_pk_add_f32 v[6:7], v[6:7], v[18:19]
	v_pk_add_f32 v[8:9], v[8:9], v[20:21]
	v_pk_add_f32 v[14:15], v[22:23], v[24:25]
	v_mov_b32_e32 v171, v13
	v_cndmask_b32_e32 v10, v195, v10, vcc
	v_pk_add_f32 v[6:7], v[6:7], v[8:9]
	v_pk_add_f32 v[8:9], v[14:15], v[170:171]
	v_lshlrev_b32_e32 v10, 2, v10
	v_pk_add_f32 v[6:7], v[6:7], v[8:9]
	ds_bpermute_b32 v8, v10, v6
	ds_bpermute_b32 v9, v10, v7
	v_cmp_lt_i32_e32 vcc, v178, v11
	v_cvt_pk_f16_f32 v15, v4, v5
	v_cvt_pk_f16_f32 v13, v150, v151
	v_cndmask_b32_e32 v11, v195, v178, vcc
	v_lshlrev_b32_e32 v11, 2, v11
	s_waitcnt lgkmcnt(0)
	v_pk_add_f32 v[4:5], v[6:7], v[8:9]
	ds_bpermute_b32 v6, v11, v4
	ds_bpermute_b32 v7, v11, v5
	v_cvt_pk_f16_f32 v14, v144, v145
	v_cvt_pk_f16_f32 v12, v148, v149
	global_store_dwordx4 v[16:17], v[12:15], off offset:256
	s_and_saveexec_b64 s[34:35], s[8:9]
	s_cbranch_execz .LBB0_481
	s_waitcnt lgkmcnt(0)
	v_pk_add_f32 v[4:5], v[4:5], v[6:7]
	s_lshl_b32 s36, s6, 2
	v_lshlrev_b64 v[6:7], 8, v[2:3]
	s_ashr_i32 s37, s36, 31
	v_lshl_add_u64 v[6:7], s[0:1], 0, v[6:7]
	v_lshl_add_u64 v[6:7], s[36:37], 3, v[6:7]
	s_lshl_b32 s12, s42, 3
	v_lshl_add_u64 v[6:7], v[6:7], 0, s[12:13]
	global_store_dwordx2 v[6:7], v[4:5], off
;     __device__ __forceinline__ void operator()(f32x4 (&acc)[2][2][4][2], const pg8::Unit& u, int wr, int wc, int fr, int fq) const {
;     ...
;                 const int row = row0 + ai * 128 + m * 16; const size_t off = (size_t)row * D + col0;
;                 float s = 0.f, q = 0.f;
; #pragma unroll
;                 for (int bj = 0; bj < 2; ++bj) {
;                     const f32x4 x0 = *(const f32x4*)(x + off + bj * 128), x1 = *(const f32x4*)(x + off + bj * 128 + 4);
;                     const f32x4 z0 = x0 * DN_ALPHA + acc[ai][bj][m][0] * ascale, z1 = x1 * DN_ALPHA + acc[ai][bj][m][1] * ascale;
;                     *(h8*)(z16 + off + bj * 128) = (h8){(_Float16)z0[0], (_Float16)z0[1], (_Float16)z0[2], (_Float16)z0[3], (_Float16)z1[0], (_Float16)z1[1], (_Float16)z1[2], (_Float16)z1[3]};
;                     s += ((z0[0] + z0[1]) + (z0[2] + z0[3])) + ((z1[0] + z1[1]) + (z1[2] + z1[3]));
;                     q += ((z0[0] * z0[0] + z0[1] * z0[1]) + (z0[2] * z0[2] + z0[3] * z0[3])) + ((z1[0] * z1[0] + z1[1] * z1[1]) + (z1[2] * z1[2] + z1[3] * z1[3]));
;                 }
;                 s += __shfl_xor(s, 16); s += __shfl_xor(s, 32); q += __shfl_xor(q, 16); q += __shfl_xor(q, 32);
;                 if (fq == 0) stats[(size_t)row * 32 + u.pn * 4 + wc] = (f32x2){s, q};
;                 asm volatile("" ::: "memory");
.LBB0_481:
	s_or_b64 exec, exec, s[34:35]
	v_or_b32_e32 v4, 16, v2
	v_ashrrev_i32_e32 v5, 31, v4
	s_waitcnt lgkmcnt(0)
	v_lshlrev_b64 v[6:7], 11, v[4:5]
	v_lshl_add_u64 v[16:17], v[6:7], 0, v[0:1]
	v_lshl_add_u64 v[18:19], v[16:17], 2, s[4:5]
	global_load_dwordx4 v[6:9], v[18:19], off nt
	global_load_dwordx4 v[12:15], v[18:19], off offset:16 nt
	v_lshl_add_u64 v[16:17], v[16:17], 1, s[96:97]
	s_waitcnt vmcnt(1)
	v_pk_mul_f32 v[8:9], v[8:9], s[20:21] op_sel_hi:[1,0]
	v_pk_mul_f32 v[6:7], v[6:7], s[20:21] op_sel_hi:[1,0]
	s_waitcnt vmcnt(0)
	v_pk_mul_f32 v[14:15], v[14:15], s[20:21] op_sel_hi:[1,0]
	v_pk_mul_f32 v[12:13], v[12:13], s[20:21] op_sel_hi:[1,0]
	v_pk_fma_f32 v[20:21], v[142:143], s[22:23], v[8:9] op_sel_hi:[1,0,1]
	v_pk_fma_f32 v[22:23], v[140:141], s[22:23], v[6:7] op_sel_hi:[1,0,1]
	v_pk_fma_f32 v[24:25], v[138:139], s[22:23], v[14:15] op_sel_hi:[1,0,1]
	v_pk_fma_f32 v[26:27], v[136:137], s[22:23], v[12:13] op_sel_hi:[1,0,1]
	v_cvt_pk_f16_f32 v9, v24, v25
	v_cvt_pk_f16_f32 v7, v20, v21
	v_cvt_pk_f16_f32 v8, v26, v27
	v_cvt_pk_f16_f32 v6, v22, v23
	global_store_dwordx4 v[16:17], v[6:9], off
	global_load_dwordx4 v[6:9], v[18:19], off offset:512 nt
	s_nop 0
	global_load_dwordx4 v[12:15], v[18:19], off offset:528 nt
	v_add_f32_e32 v18, v22, v23
	v_add_f32_e32 v28, v20, v21
	v_add_f32_e32 v30, v26, v27
	v_add_f32_e32 v136, v24, v25
	v_mul_f32_e32 v139, v22, v22
	v_mul_f32_e32 v23, v23, v23
	v_mul_f32_e32 v141, v20, v20
	v_mul_f32_e32 v21, v21, v21
	v_mul_f32_e32 v143, v26, v26
	v_mul_f32_e32 v27, v27, v27
	v_mul_f32_e32 v145, v24, v24
	v_mul_f32_e32 v25, v25, v25
	s_waitcnt vmcnt(1)
	v_pk_mul_f32 v[6:7], v[6:7], s[20:21] op_sel_hi:[1,0]
	s_waitcnt vmcnt(0)
	v_pk_mul_f32 v[14:15], v[14:15], s[20:21] op_sel_hi:[1,0]
	v_pk_mul_f32 v[12:13], v[12:13], s[20:21] op_sel_hi:[1,0]
	v_pk_mul_f32 v[8:9], v[8:9], s[20:21] op_sel_hi:[1,0]
	v_pk_fma_f32 v[132:133], v[132:133], s[22:23], v[6:7] op_sel_hi:[1,0,1]
	v_pk_fma_f32 v[6:7], v[130:131], s[22:23], v[14:15] op_sel_hi:[1,0,1]
	v_pk_fma_f32 v[128:129], v[128:129], s[22:23], v[12:13] op_sel_hi:[1,0,1]
	v_pk_fma_f32 v[134:135], v[134:135], s[22:23], v[8:9] op_sel_hi:[1,0,1]
	v_pk_mul_f32 v[8:9], v[6:7], v[6:7]
	v_pk_mul_f32 v[12:13], v[128:129], v[128:129]
	v_mul_f32_e32 v19, v132, v132
	v_pk_mov_b32 v[14:15], v[12:13], v[8:9] op_sel:[1,0]
	v_mov_b32_e32 v13, v9
	v_mul_f32_e32 v29, v133, v133
	v_mul_f32_e32 v31, v134, v134
	v_mul_f32_e32 v137, v135, v135
	v_mov_b32_e32 v138, v132
	v_mov_b32_e32 v22, v133
	v_mov_b32_e32 v140, v134
	v_mov_b32_e32 v20, v135
	v_mov_b32_e32 v142, v128
	v_mov_b32_e32 v26, v129
	v_mov_b32_e32 v144, v6
	v_mov_b32_e32 v24, v7
	v_pk_add_f32 v[12:13], v[14:15], v[12:13]
	v_pk_add_f32 v[8:9], v[138:139], v[22:23]
	v_pk_add_f32 v[20:21], v[140:141], v[20:21]
	v_pk_add_f32 v[22:23], v[142:143], v[26:27]
	v_pk_add_f32 v[24:25], v[144:145], v[24:25]
	v_pk_add_f32 v[18:19], v[18:19], v[28:29]
	v_pk_add_f32 v[26:27], v[30:31], v[136:137]
	v_pk_add_f32 v[12:13], v[12:13], v[12:13] op_sel_hi:[0,1]
	v_pk_add_f32 v[8:9], v[8:9], v[20:21]
	v_pk_add_f32 v[14:15], v[22:23], v[24:25]
	v_pk_add_f32 v[18:19], v[18:19], v[26:27]
	v_mov_b32_e32 v171, v13
	v_pk_add_f32 v[8:9], v[8:9], v[14:15]
	v_pk_add_f32 v[12:13], v[18:19], v[170:171]
	v_cvt_pk_f16_f32 v15, v6, v7
	v_pk_add_f32 v[8:9], v[8:9], v[12:13]
	ds_bpermute_b32 v12, v10, v8
	ds_bpermute_b32 v13, v10, v9
	v_cvt_pk_f16_f32 v14, v128, v129
	s_waitcnt lgkmcnt(0)
	v_pk_add_f32 v[6:7], v[8:9], v[12:13]
	ds_bpermute_b32 v8, v11, v6
	ds_bpermute_b32 v9, v11, v7
	v_cvt_pk_f16_f32 v13, v134, v135
	v_cvt_pk_f16_f32 v12, v132, v133
	global_store_dwordx4 v[16:17], v[12:15], off offset:256
	s_and_saveexec_b64 s[34:35], s[8:9]
	s_cbranch_execz .LBB0_483
	s_lshl_b32 s36, s6, 2
	v_lshlrev_b64 v[4:5], 8, v[4:5]
	s_ashr_i32 s37, s36, 31
	v_lshl_add_u64 v[4:5], s[0:1], 0, v[4:5]
	v_lshl_add_u64 v[4:5], s[36:37], 3, v[4:5]
	s_lshl_b32 s12, s42, 3
	s_waitcnt lgkmcnt(0)
	v_pk_add_f32 v[6:7], v[6:7], v[8:9]
	v_lshl_add_u64 v[4:5], v[4:5], 0, s[12:13]
	global_store_dwordx2 v[4:5], v[6:7], off
.LBB0_483:
	s_or_b64 exec, exec, s[34:35]
	v_or_b32_e32 v4, 32, v2
	v_ashrrev_i32_e32 v5, 31, v4
	v_lshlrev_b64 v[6:7], 11, v[4:5]
	v_lshl_add_u64 v[16:17], v[6:7], 0, v[0:1]
	v_lshl_add_u64 v[18:19], v[16:17], 2, s[4:5]
	s_waitcnt lgkmcnt(0)
	global_load_dwordx4 v[6:9], v[18:19], off nt
	global_load_dwordx4 v[12:15], v[18:19], off offset:16 nt
	v_lshl_add_u64 v[16:17], v[16:17], 1, s[96:97]
	s_waitcnt vmcnt(1)
	v_pk_mul_f32 v[8:9], v[8:9], s[20:21] op_sel_hi:[1,0]
	v_pk_mul_f32 v[6:7], v[6:7], s[20:21] op_sel_hi:[1,0]
	s_waitcnt vmcnt(0)
	v_pk_mul_f32 v[14:15], v[14:15], s[20:21] op_sel_hi:[1,0]
	v_pk_mul_f32 v[12:13], v[12:13], s[20:21] op_sel_hi:[1,0]
	v_pk_fma_f32 v[20:21], v[126:127], s[22:23], v[8:9] op_sel_hi:[1,0,1]
	v_pk_fma_f32 v[22:23], v[124:125], s[22:23], v[6:7] op_sel_hi:[1,0,1]
	v_pk_fma_f32 v[24:25], v[122:123], s[22:23], v[14:15] op_sel_hi:[1,0,1]
	v_pk_fma_f32 v[26:27], v[120:121], s[22:23], v[12:13] op_sel_hi:[1,0,1]
	v_cvt_pk_f16_f32 v9, v24, v25
	v_cvt_pk_f16_f32 v7, v20, v21
	v_cvt_pk_f16_f32 v8, v26, v27
	v_cvt_pk_f16_f32 v6, v22, v23
	global_store_dwordx4 v[16:17], v[6:9], off
	global_load_dwordx4 v[6:9], v[18:19], off offset:512 nt
	s_nop 0
	global_load_dwordx4 v[12:15], v[18:19], off offset:528 nt
	v_add_f32_e32 v18, v22, v23
	v_add_f32_e32 v28, v20, v21
	v_add_f32_e32 v30, v26, v27
	v_add_f32_e32 v120, v24, v25
	v_mul_f32_e32 v123, v22, v22
	v_mul_f32_e32 v23, v23, v23
	v_mul_f32_e32 v125, v20, v20
	v_mul_f32_e32 v21, v21, v21
	v_mul_f32_e32 v127, v26, v26
	v_mul_f32_e32 v27, v27, v27
	v_mul_f32_e32 v129, v24, v24
	v_mul_f32_e32 v25, v25, v25
	s_waitcnt vmcnt(1)
;     __device__ __forceinline__ void operator()(f32x4 (&acc)[2][2][4][2], const pg8::Unit& u, int wr, int wc, int fr, int fq) const {
;     ...
;                 const int row = row0 + ai * 128 + m * 16; const size_t off = (size_t)row * D + col0;
;                 float s = 0.f, q = 0.f;
; #pragma unroll
;                 for (int bj = 0; bj < 2; ++bj) {
;                     const f32x4 x0 = *(const f32x4*)(x + off + bj * 128), x1 = *(const f32x4*)(x + off + bj * 128 + 4);
;                     const f32x4 z0 = x0 * DN_ALPHA + acc[ai][bj][m][0] * ascale, z1 = x1 * DN_ALPHA + acc[ai][bj][m][1] * ascale;
;                     *(h8*)(z16 + off + bj * 128) = (h8){(_Float16)z0[0], (_Float16)z0[1], (_Float16)z0[2], (_Float16)z0[3], (_Float16)z1[0], (_Float16)z1[1], (_Float16)z1[2], (_Float16)z1[3]};
;                     s += ((z0[0] + z0[1]) + (z0[2] + z0[3])) + ((z1[0] + z1[1]) + (z1[2] + z1[3]));
;                     q += ((z0[0] * z0[0] + z0[1] * z0[1]) + (z0[2] * z0[2] + z0[3] * z0[3])) + ((z1[0] * z1[0] + z1[1] * z1[1]) + (z1[2] * z1[2] + z1[3] * z1[3]));
;                 }
;                 s += __shfl_xor(s, 16); s += __shfl_xor(s, 32); q += __shfl_xor(q, 16); q += __shfl_xor(q, 32);
;                 if (fq == 0) stats[(size_t)row * 32 + u.pn * 4 + wc] = (f32x2){s, q};
;                 asm volatile("" ::: "memory");
	v_pk_mul_f32 v[6:7], v[6:7], s[20:21] op_sel_hi:[1,0]
	s_waitcnt vmcnt(0)
	v_pk_mul_f32 v[14:15], v[14:15], s[20:21] op_sel_hi:[1,0]
	v_pk_mul_f32 v[12:13], v[12:13], s[20:21] op_sel_hi:[1,0]
	v_pk_mul_f32 v[8:9], v[8:9], s[20:21] op_sel_hi:[1,0]
	v_pk_fma_f32 v[116:117], v[116:117], s[22:23], v[6:7] op_sel_hi:[1,0,1]
	v_pk_fma_f32 v[6:7], v[114:115], s[22:23], v[14:15] op_sel_hi:[1,0,1]
	v_pk_fma_f32 v[112:113], v[112:113], s[22:23], v[12:13] op_sel_hi:[1,0,1]
	v_pk_fma_f32 v[118:119], v[118:119], s[22:23], v[8:9] op_sel_hi:[1,0,1]
	v_pk_mul_f32 v[8:9], v[6:7], v[6:7]
	v_pk_mul_f32 v[12:13], v[112:113], v[112:113]
	v_mul_f32_e32 v19, v116, v116
	v_pk_mov_b32 v[14:15], v[12:13], v[8:9] op_sel:[1,0]
	v_mov_b32_e32 v13, v9
	v_mul_f32_e32 v29, v117, v117
	v_mul_f32_e32 v31, v118, v118
	v_mul_f32_e32 v121, v119, v119
	v_mov_b32_e32 v122, v116
	v_mov_b32_e32 v22, v117
	v_mov_b32_e32 v124, v118
	v_mov_b32_e32 v20, v119
	v_mov_b32_e32 v126, v112
	v_mov_b32_e32 v26, v113
	v_mov_b32_e32 v128, v6
	v_mov_b32_e32 v24, v7
	v_pk_add_f32 v[12:13], v[14:15], v[12:13]
	v_pk_add_f32 v[8:9], v[122:123], v[22:23]
	v_pk_add_f32 v[20:21], v[124:125], v[20:21]
	v_pk_add_f32 v[22:23], v[126:127], v[26:27]
	v_pk_add_f32 v[24:25], v[128:129], v[24:25]
	v_pk_add_f32 v[18:19], v[18:19], v[28:29]
	v_pk_add_f32 v[26:27], v[30:31], v[120:121]
	v_pk_add_f32 v[12:13], v[12:13], v[12:13] op_sel_hi:[0,1]
	v_pk_add_f32 v[8:9], v[8:9], v[20:21]
	v_pk_add_f32 v[14:15], v[22:23], v[24:25]
	v_pk_add_f32 v[18:19], v[18:19], v[26:27]
	v_mov_b32_e32 v171, v13
	v_pk_add_f32 v[8:9], v[8:9], v[14:15]
	v_pk_add_f32 v[12:13], v[18:19], v[170:171]
	v_cvt_pk_f16_f32 v15, v6, v7
	v_pk_add_f32 v[8:9], v[8:9], v[12:13]
	ds_bpermute_b32 v12, v10, v8
	ds_bpermute_b32 v13, v10, v9
	v_cvt_pk_f16_f32 v14, v112, v113
	s_waitcnt lgkmcnt(0)
	v_pk_add_f32 v[6:7], v[8:9], v[12:13]
	ds_bpermute_b32 v8, v11, v6
	ds_bpermute_b32 v9, v11, v7
	v_cvt_pk_f16_f32 v13, v118, v119
	v_cvt_pk_f16_f32 v12, v116, v117
	global_store_dwordx4 v[16:17], v[12:15], off offset:256
	s_and_saveexec_b64 s[34:35], s[8:9]
	s_cbranch_execz .LBB0_485
	s_lshl_b32 s36, s6, 2
	v_lshlrev_b64 v[4:5], 8, v[4:5]
	s_ashr_i32 s37, s36, 31
	v_lshl_add_u64 v[4:5], s[0:1], 0, v[4:5]
	v_lshl_add_u64 v[4:5], s[36:37], 3, v[4:5]
	s_lshl_b32 s12, s42, 3
	s_waitcnt lgkmcnt(0)
	v_pk_add_f32 v[6:7], v[6:7], v[8:9]
	v_lshl_add_u64 v[4:5], v[4:5], 0, s[12:13]
	global_store_dwordx2 v[4:5], v[6:7], off
.LBB0_485:
	s_or_b64 exec, exec, s[34:35]
	v_or_b32_e32 v4, 48, v2
	v_ashrrev_i32_e32 v5, 31, v4
	v_lshlrev_b64 v[6:7], 11, v[4:5]
	v_lshl_add_u64 v[16:17], v[6:7], 0, v[0:1]
	v_lshl_add_u64 v[18:19], v[16:17], 2, s[4:5]
	s_waitcnt lgkmcnt(0)
	global_load_dwordx4 v[6:9], v[18:19], off nt
	global_load_dwordx4 v[12:15], v[18:19], off offset:16 nt
	v_lshl_add_u64 v[16:17], v[16:17], 1, s[96:97]
	s_waitcnt vmcnt(1)
	v_pk_mul_f32 v[8:9], v[8:9], s[20:21] op_sel_hi:[1,0]
	v_pk_mul_f32 v[6:7], v[6:7], s[20:21] op_sel_hi:[1,0]
	s_waitcnt vmcnt(0)
	v_pk_mul_f32 v[14:15], v[14:15], s[20:21] op_sel_hi:[1,0]
	v_pk_mul_f32 v[12:13], v[12:13], s[20:21] op_sel_hi:[1,0]
	v_pk_fma_f32 v[20:21], v[110:111], s[22:23], v[8:9] op_sel_hi:[1,0,1]
	v_pk_fma_f32 v[22:23], v[108:109], s[22:23], v[6:7] op_sel_hi:[1,0,1]
	v_pk_fma_f32 v[24:25], v[106:107], s[22:23], v[14:15] op_sel_hi:[1,0,1]
	v_pk_fma_f32 v[26:27], v[104:105], s[22:23], v[12:13] op_sel_hi:[1,0,1]
	v_cvt_pk_f16_f32 v9, v24, v25
	v_cvt_pk_f16_f32 v7, v20, v21
	v_cvt_pk_f16_f32 v8, v26, v27
	v_cvt_pk_f16_f32 v6, v22, v23
	global_store_dwordx4 v[16:17], v[6:9], off
	global_load_dwordx4 v[6:9], v[18:19], off offset:512 nt
	s_nop 0
	global_load_dwordx4 v[12:15], v[18:19], off offset:528 nt
	v_add_f32_e32 v18, v22, v23
	v_add_f32_e32 v28, v20, v21
	v_add_f32_e32 v30, v26, v27
	v_add_f32_e32 v104, v24, v25
	v_mul_f32_e32 v107, v22, v22
	v_mul_f32_e32 v23, v23, v23
	v_mul_f32_e32 v109, v20, v20
	v_mul_f32_e32 v21, v21, v21
	v_mul_f32_e32 v111, v26, v26
	v_mul_f32_e32 v27, v27, v27
	v_mul_f32_e32 v113, v24, v24
	v_mul_f32_e32 v25, v25, v25
	s_waitcnt vmcnt(1)
	v_pk_mul_f32 v[6:7], v[6:7], s[20:21] op_sel_hi:[1,0]
	s_waitcnt vmcnt(0)
	v_pk_mul_f32 v[14:15], v[14:15], s[20:21] op_sel_hi:[1,0]
	v_pk_mul_f32 v[12:13], v[12:13], s[20:21] op_sel_hi:[1,0]
	v_pk_mul_f32 v[8:9], v[8:9], s[20:21] op_sel_hi:[1,0]
	v_pk_fma_f32 v[100:101], v[100:101], s[22:23], v[6:7] op_sel_hi:[1,0,1]
	v_pk_fma_f32 v[6:7], v[98:99], s[22:23], v[14:15] op_sel_hi:[1,0,1]
	v_pk_fma_f32 v[96:97], v[96:97], s[22:23], v[12:13] op_sel_hi:[1,0,1]
	v_pk_fma_f32 v[102:103], v[102:103], s[22:23], v[8:9] op_sel_hi:[1,0,1]
	v_pk_mul_f32 v[8:9], v[6:7], v[6:7]
	v_pk_mul_f32 v[12:13], v[96:97], v[96:97]
	v_mul_f32_e32 v19, v100, v100
	v_pk_mov_b32 v[14:15], v[12:13], v[8:9] op_sel:[1,0]
	v_mov_b32_e32 v13, v9
	v_mul_f32_e32 v29, v101, v101
	v_mul_f32_e32 v31, v102, v102
	v_mul_f32_e32 v105, v103, v103
	v_mov_b32_e32 v106, v100
	v_mov_b32_e32 v22, v101
	v_mov_b32_e32 v108, v102
	v_mov_b32_e32 v20, v103
	v_mov_b32_e32 v110, v96
	v_mov_b32_e32 v26, v97
	v_mov_b32_e32 v112, v6
	v_mov_b32_e32 v24, v7
	v_pk_add_f32 v[12:13], v[14:15], v[12:13]
	v_pk_add_f32 v[8:9], v[106:107], v[22:23]
	v_pk_add_f32 v[20:21], v[108:109], v[20:21]
	v_pk_add_f32 v[22:23], v[110:111], v[26:27]
	v_pk_add_f32 v[24:25], v[112:113], v[24:25]
	v_pk_add_f32 v[18:19], v[18:19], v[28:29]
	v_pk_add_f32 v[26:27], v[30:31], v[104:105]
	v_pk_add_f32 v[12:13], v[12:13], v[12:13] op_sel_hi:[0,1]
	v_pk_add_f32 v[8:9], v[8:9], v[20:21]
	v_pk_add_f32 v[14:15], v[22:23], v[24:25]
	v_pk_add_f32 v[18:19], v[18:19], v[26:27]
	v_mov_b32_e32 v171, v13
	v_pk_add_f32 v[8:9], v[8:9], v[14:15]
	v_pk_add_f32 v[12:13], v[18:19], v[170:171]
	v_cvt_pk_f16_f32 v15, v6, v7
	v_pk_add_f32 v[8:9], v[8:9], v[12:13]
	ds_bpermute_b32 v12, v10, v8
	ds_bpermute_b32 v13, v10, v9
	v_cvt_pk_f16_f32 v14, v96, v97
	s_waitcnt lgkmcnt(0)
	v_pk_add_f32 v[6:7], v[8:9], v[12:13]
	ds_bpermute_b32 v8, v11, v6
	ds_bpermute_b32 v9, v11, v7
	v_cvt_pk_f16_f32 v13, v102, v103
	v_cvt_pk_f16_f32 v12, v100, v101
	global_store_dwordx4 v[16:17], v[12:15], off offset:256
	s_and_saveexec_b64 s[34:35], s[8:9]
	s_cbranch_execz .LBB0_487
	s_lshl_b32 s36, s6, 2
	v_lshlrev_b64 v[4:5], 8, v[4:5]
	s_ashr_i32 s37, s36, 31
	v_lshl_add_u64 v[4:5], s[0:1], 0, v[4:5]
	v_lshl_add_u64 v[4:5], s[36:37], 3, v[4:5]
	s_lshl_b32 s12, s42, 3
	s_waitcnt lgkmcnt(0)
	v_pk_add_f32 v[6:7], v[6:7], v[8:9]
	v_lshl_add_u64 v[4:5], v[4:5], 0, s[12:13]
	global_store_dwordx2 v[4:5], v[6:7], off
;     __device__ __forceinline__ void operator()(f32x4 (&acc)[2][2][4][2], const pg8::Unit& u, int wr, int wc, int fr, int fq) const {
;     ...
;                 const int row = row0 + ai * 128 + m * 16; const size_t off = (size_t)row * D + col0;
;                 float s = 0.f, q = 0.f;
; #pragma unroll
;                 for (int bj = 0; bj < 2; ++bj) {
;                     const f32x4 x0 = *(const f32x4*)(x + off + bj * 128), x1 = *(const f32x4*)(x + off + bj * 128 + 4);
;                     const f32x4 z0 = x0 * DN_ALPHA + acc[ai][bj][m][0] * ascale, z1 = x1 * DN_ALPHA + acc[ai][bj][m][1] * ascale;
;                     *(h8*)(z16 + off + bj * 128) = (h8){(_Float16)z0[0], (_Float16)z0[1], (_Float16)z0[2], (_Float16)z0[3], (_Float16)z1[0], (_Float16)z1[1], (_Float16)z1[2], (_Float16)z1[3]};
;                     s += ((z0[0] + z0[1]) + (z0[2] + z0[3])) + ((z1[0] + z1[1]) + (z1[2] + z1[3]));
;                     q += ((z0[0] * z0[0] + z0[1] * z0[1]) + (z0[2] * z0[2] + z0[3] * z0[3])) + ((z1[0] * z1[0] + z1[1] * z1[1]) + (z1[2] * z1[2] + z1[3] * z1[3]));
;                 }
;                 s += __shfl_xor(s, 16); s += __shfl_xor(s, 32); q += __shfl_xor(q, 16); q += __shfl_xor(q, 32);
;                 if (fq == 0) stats[(size_t)row * 32 + u.pn * 4 + wc] = (f32x2){s, q};
;                 asm volatile("" ::: "memory");
.LBB0_487:
	s_or_b64 exec, exec, s[34:35]
	v_add_u32_e32 v4, 0x80, v2
	v_ashrrev_i32_e32 v5, 31, v4
	v_lshlrev_b64 v[6:7], 11, v[4:5]
	v_lshl_add_u64 v[16:17], v[6:7], 0, v[0:1]
	v_lshl_add_u64 v[18:19], v[16:17], 2, s[4:5]
	s_waitcnt lgkmcnt(0)
	global_load_dwordx4 v[6:9], v[18:19], off nt
	global_load_dwordx4 v[12:15], v[18:19], off offset:16 nt
	v_lshl_add_u64 v[16:17], v[16:17], 1, s[96:97]
	s_waitcnt vmcnt(1)
	v_pk_mul_f32 v[8:9], v[8:9], s[20:21] op_sel_hi:[1,0]
	v_pk_mul_f32 v[6:7], v[6:7], s[20:21] op_sel_hi:[1,0]
	s_waitcnt vmcnt(0)
	v_pk_mul_f32 v[14:15], v[14:15], s[20:21] op_sel_hi:[1,0]
	v_pk_mul_f32 v[12:13], v[12:13], s[20:21] op_sel_hi:[1,0]
	v_pk_fma_f32 v[20:21], v[94:95], s[22:23], v[8:9] op_sel_hi:[1,0,1]
	v_pk_fma_f32 v[22:23], v[92:93], s[22:23], v[6:7] op_sel_hi:[1,0,1]
	v_pk_fma_f32 v[24:25], v[90:91], s[22:23], v[14:15] op_sel_hi:[1,0,1]
	v_pk_fma_f32 v[26:27], v[88:89], s[22:23], v[12:13] op_sel_hi:[1,0,1]
	v_cvt_pk_f16_f32 v9, v24, v25
	v_cvt_pk_f16_f32 v7, v20, v21
	v_cvt_pk_f16_f32 v8, v26, v27
	v_cvt_pk_f16_f32 v6, v22, v23
	global_store_dwordx4 v[16:17], v[6:9], off
	global_load_dwordx4 v[6:9], v[18:19], off offset:512 nt
	s_nop 0
	global_load_dwordx4 v[12:15], v[18:19], off offset:528 nt
	v_add_f32_e32 v18, v22, v23
	v_add_f32_e32 v28, v20, v21
	v_add_f32_e32 v30, v26, v27
	v_add_f32_e32 v88, v24, v25
	v_mul_f32_e32 v91, v22, v22
	v_mul_f32_e32 v23, v23, v23
	v_mul_f32_e32 v93, v20, v20
	v_mul_f32_e32 v21, v21, v21
	v_mul_f32_e32 v95, v26, v26
	v_mul_f32_e32 v27, v27, v27
	v_mul_f32_e32 v97, v24, v24
	v_mul_f32_e32 v25, v25, v25
	s_waitcnt vmcnt(1)
	v_pk_mul_f32 v[6:7], v[6:7], s[20:21] op_sel_hi:[1,0]
	s_waitcnt vmcnt(0)
	v_pk_mul_f32 v[14:15], v[14:15], s[20:21] op_sel_hi:[1,0]
	v_pk_mul_f32 v[12:13], v[12:13], s[20:21] op_sel_hi:[1,0]
	v_pk_mul_f32 v[8:9], v[8:9], s[20:21] op_sel_hi:[1,0]
	v_pk_fma_f32 v[84:85], v[84:85], s[22:23], v[6:7] op_sel_hi:[1,0,1]
	v_pk_fma_f32 v[6:7], v[82:83], s[22:23], v[14:15] op_sel_hi:[1,0,1]
	v_pk_fma_f32 v[80:81], v[80:81], s[22:23], v[12:13] op_sel_hi:[1,0,1]
	v_pk_fma_f32 v[86:87], v[86:87], s[22:23], v[8:9] op_sel_hi:[1,0,1]
	v_pk_mul_f32 v[8:9], v[6:7], v[6:7]
	v_pk_mul_f32 v[12:13], v[80:81], v[80:81]
	v_mul_f32_e32 v19, v84, v84
	v_pk_mov_b32 v[14:15], v[12:13], v[8:9] op_sel:[1,0]
	v_mov_b32_e32 v13, v9
	v_mul_f32_e32 v29, v85, v85
	v_mul_f32_e32 v31, v86, v86
	v_mul_f32_e32 v89, v87, v87
	v_mov_b32_e32 v90, v84
	v_mov_b32_e32 v22, v85
	v_mov_b32_e32 v92, v86
	v_mov_b32_e32 v20, v87
	v_mov_b32_e32 v94, v80
	v_mov_b32_e32 v26, v81
	v_mov_b32_e32 v96, v6
	v_mov_b32_e32 v24, v7
	v_pk_add_f32 v[12:13], v[14:15], v[12:13]
	v_pk_add_f32 v[8:9], v[90:91], v[22:23]
	v_pk_add_f32 v[20:21], v[92:93], v[20:21]
	v_pk_add_f32 v[22:23], v[94:95], v[26:27]
	v_pk_add_f32 v[24:25], v[96:97], v[24:25]
	v_pk_add_f32 v[18:19], v[18:19], v[28:29]
	v_pk_add_f32 v[26:27], v[30:31], v[88:89]
	v_pk_add_f32 v[12:13], v[12:13], v[12:13] op_sel_hi:[0,1]
	v_pk_add_f32 v[8:9], v[8:9], v[20:21]
	v_pk_add_f32 v[14:15], v[22:23], v[24:25]
	v_pk_add_f32 v[18:19], v[18:19], v[26:27]
	v_mov_b32_e32 v171, v13
	v_pk_add_f32 v[8:9], v[8:9], v[14:15]
	v_pk_add_f32 v[12:13], v[18:19], v[170:171]
	v_cvt_pk_f16_f32 v15, v6, v7
	v_pk_add_f32 v[8:9], v[8:9], v[12:13]
	ds_bpermute_b32 v12, v10, v8
	ds_bpermute_b32 v13, v10, v9
	v_cvt_pk_f16_f32 v14, v80, v81
	s_waitcnt lgkmcnt(0)
	v_pk_add_f32 v[6:7], v[8:9], v[12:13]
	ds_bpermute_b32 v8, v11, v6
	ds_bpermute_b32 v9, v11, v7
	v_cvt_pk_f16_f32 v13, v86, v87
	v_cvt_pk_f16_f32 v12, v84, v85
	global_store_dwordx4 v[16:17], v[12:15], off offset:256
	s_and_saveexec_b64 s[34:35], s[8:9]
	s_cbranch_execz .LBB0_489
	s_lshl_b32 s36, s6, 2
	v_lshlrev_b64 v[4:5], 8, v[4:5]
	s_ashr_i32 s37, s36, 31
	v_lshl_add_u64 v[4:5], s[0:1], 0, v[4:5]
	v_lshl_add_u64 v[4:5], s[36:37], 3, v[4:5]
	s_lshl_b32 s12, s42, 3
	s_waitcnt lgkmcnt(0)
	v_pk_add_f32 v[6:7], v[6:7], v[8:9]
	v_lshl_add_u64 v[4:5], v[4:5], 0, s[12:13]
	global_store_dwordx2 v[4:5], v[6:7], off
.LBB0_489:
	s_or_b64 exec, exec, s[34:35]
	v_add_u32_e32 v4, 0x90, v2
	v_ashrrev_i32_e32 v5, 31, v4
	v_lshlrev_b64 v[6:7], 11, v[4:5]
	v_lshl_add_u64 v[16:17], v[6:7], 0, v[0:1]
	v_lshl_add_u64 v[18:19], v[16:17], 2, s[4:5]
	s_waitcnt lgkmcnt(0)
	global_load_dwordx4 v[6:9], v[18:19], off nt
	global_load_dwordx4 v[12:15], v[18:19], off offset:16 nt
	v_lshl_add_u64 v[16:17], v[16:17], 1, s[96:97]
	s_waitcnt vmcnt(1)
	v_pk_mul_f32 v[8:9], v[8:9], s[20:21] op_sel_hi:[1,0]
	v_pk_mul_f32 v[6:7], v[6:7], s[20:21] op_sel_hi:[1,0]
	s_waitcnt vmcnt(0)
	v_pk_mul_f32 v[14:15], v[14:15], s[20:21] op_sel_hi:[1,0]
	v_pk_mul_f32 v[12:13], v[12:13], s[20:21] op_sel_hi:[1,0]
	v_pk_fma_f32 v[20:21], v[78:79], s[22:23], v[8:9] op_sel_hi:[1,0,1]
	v_pk_fma_f32 v[22:23], v[76:77], s[22:23], v[6:7] op_sel_hi:[1,0,1]
	v_pk_fma_f32 v[24:25], v[74:75], s[22:23], v[14:15] op_sel_hi:[1,0,1]
	v_pk_fma_f32 v[26:27], v[72:73], s[22:23], v[12:13] op_sel_hi:[1,0,1]
	v_cvt_pk_f16_f32 v9, v24, v25
	v_cvt_pk_f16_f32 v7, v20, v21
	v_cvt_pk_f16_f32 v8, v26, v27
	v_cvt_pk_f16_f32 v6, v22, v23
	global_store_dwordx4 v[16:17], v[6:9], off
	global_load_dwordx4 v[6:9], v[18:19], off offset:512 nt
	s_nop 0
	global_load_dwordx4 v[12:15], v[18:19], off offset:528 nt
	v_add_f32_e32 v18, v22, v23
	v_add_f32_e32 v28, v20, v21
	v_add_f32_e32 v30, v26, v27
	v_add_f32_e32 v72, v24, v25
	v_mul_f32_e32 v75, v22, v22
	v_mul_f32_e32 v23, v23, v23
	v_mul_f32_e32 v77, v20, v20
	v_mul_f32_e32 v21, v21, v21
	v_mul_f32_e32 v79, v26, v26
	v_mul_f32_e32 v27, v27, v27
	v_mul_f32_e32 v81, v24, v24
	v_mul_f32_e32 v25, v25, v25
	s_waitcnt vmcnt(1)
	v_pk_mul_f32 v[6:7], v[6:7], s[20:21] op_sel_hi:[1,0]
	s_waitcnt vmcnt(0)
;     __device__ __forceinline__ void operator()(f32x4 (&acc)[2][2][4][2], const pg8::Unit& u, int wr, int wc, int fr, int fq) const {
;     ...
;                 const int row = row0 + ai * 128 + m * 16; const size_t off = (size_t)row * D + col0;
;                 float s = 0.f, q = 0.f;
; #pragma unroll
;                 for (int bj = 0; bj < 2; ++bj) {
;                     const f32x4 x0 = *(const f32x4*)(x + off + bj * 128), x1 = *(const f32x4*)(x + off + bj * 128 + 4);
;                     const f32x4 z0 = x0 * DN_ALPHA + acc[ai][bj][m][0] * ascale, z1 = x1 * DN_ALPHA + acc[ai][bj][m][1] * ascale;
;                     *(h8*)(z16 + off + bj * 128) = (h8){(_Float16)z0[0], (_Float16)z0[1], (_Float16)z0[2], (_Float16)z0[3], (_Float16)z1[0], (_Float16)z1[1], (_Float16)z1[2], (_Float16)z1[3]};
;                     s += ((z0[0] + z0[1]) + (z0[2] + z0[3])) + ((z1[0] + z1[1]) + (z1[2] + z1[3]));
;                     q += ((z0[0] * z0[0] + z0[1] * z0[1]) + (z0[2] * z0[2] + z0[3] * z0[3])) + ((z1[0] * z1[0] + z1[1] * z1[1]) + (z1[2] * z1[2] + z1[3] * z1[3]));
;                 }
;                 s += __shfl_xor(s, 16); s += __shfl_xor(s, 32); q += __shfl_xor(q, 16); q += __shfl_xor(q, 32);
;                 if (fq == 0) stats[(size_t)row * 32 + u.pn * 4 + wc] = (f32x2){s, q};
;                 asm volatile("" ::: "memory");
	v_pk_mul_f32 v[14:15], v[14:15], s[20:21] op_sel_hi:[1,0]
	v_pk_mul_f32 v[12:13], v[12:13], s[20:21] op_sel_hi:[1,0]
	v_pk_mul_f32 v[8:9], v[8:9], s[20:21] op_sel_hi:[1,0]
	v_pk_fma_f32 v[68:69], v[68:69], s[22:23], v[6:7] op_sel_hi:[1,0,1]
	v_pk_fma_f32 v[6:7], v[66:67], s[22:23], v[14:15] op_sel_hi:[1,0,1]
	v_pk_fma_f32 v[64:65], v[64:65], s[22:23], v[12:13] op_sel_hi:[1,0,1]
	v_pk_fma_f32 v[70:71], v[70:71], s[22:23], v[8:9] op_sel_hi:[1,0,1]
	v_pk_mul_f32 v[8:9], v[6:7], v[6:7]
	v_pk_mul_f32 v[12:13], v[64:65], v[64:65]
	v_mul_f32_e32 v19, v68, v68
	v_pk_mov_b32 v[14:15], v[12:13], v[8:9] op_sel:[1,0]
	v_mov_b32_e32 v13, v9
	v_mul_f32_e32 v29, v69, v69
	v_mul_f32_e32 v31, v70, v70
	v_mul_f32_e32 v73, v71, v71
	v_mov_b32_e32 v74, v68
	v_mov_b32_e32 v22, v69
	v_mov_b32_e32 v76, v70
	v_mov_b32_e32 v20, v71
	v_mov_b32_e32 v78, v64
	v_mov_b32_e32 v26, v65
	v_mov_b32_e32 v80, v6
	v_mov_b32_e32 v24, v7
	v_pk_add_f32 v[12:13], v[14:15], v[12:13]
	v_pk_add_f32 v[8:9], v[74:75], v[22:23]
	v_pk_add_f32 v[20:21], v[76:77], v[20:21]
	v_pk_add_f32 v[22:23], v[78:79], v[26:27]
	v_pk_add_f32 v[24:25], v[80:81], v[24:25]
	v_pk_add_f32 v[18:19], v[18:19], v[28:29]
	v_pk_add_f32 v[26:27], v[30:31], v[72:73]
	v_pk_add_f32 v[12:13], v[12:13], v[12:13] op_sel_hi:[0,1]
	v_pk_add_f32 v[8:9], v[8:9], v[20:21]
	v_pk_add_f32 v[14:15], v[22:23], v[24:25]
	v_pk_add_f32 v[18:19], v[18:19], v[26:27]
	v_mov_b32_e32 v171, v13
	v_pk_add_f32 v[8:9], v[8:9], v[14:15]
	v_pk_add_f32 v[12:13], v[18:19], v[170:171]
	v_cvt_pk_f16_f32 v15, v6, v7
	v_pk_add_f32 v[8:9], v[8:9], v[12:13]
	ds_bpermute_b32 v12, v10, v8
	ds_bpermute_b32 v13, v10, v9
	v_cvt_pk_f16_f32 v14, v64, v65
	s_waitcnt lgkmcnt(0)
	v_pk_add_f32 v[6:7], v[8:9], v[12:13]
	ds_bpermute_b32 v8, v11, v6
	ds_bpermute_b32 v9, v11, v7
	v_cvt_pk_f16_f32 v13, v70, v71
	v_cvt_pk_f16_f32 v12, v68, v69
	global_store_dwordx4 v[16:17], v[12:15], off offset:256
	s_and_saveexec_b64 s[34:35], s[8:9]
	s_cbranch_execz .LBB0_491
	s_lshl_b32 s36, s6, 2
	v_lshlrev_b64 v[4:5], 8, v[4:5]
	s_ashr_i32 s37, s36, 31
	v_lshl_add_u64 v[4:5], s[0:1], 0, v[4:5]
	v_lshl_add_u64 v[4:5], s[36:37], 3, v[4:5]
	s_lshl_b32 s12, s42, 3
	s_waitcnt lgkmcnt(0)
	v_pk_add_f32 v[6:7], v[6:7], v[8:9]
	v_lshl_add_u64 v[4:5], v[4:5], 0, s[12:13]
	global_store_dwordx2 v[4:5], v[6:7], off
.LBB0_491:
	s_or_b64 exec, exec, s[34:35]
	v_add_u32_e32 v4, 0xa0, v2
	v_ashrrev_i32_e32 v5, 31, v4
	v_lshlrev_b64 v[6:7], 11, v[4:5]
	v_lshl_add_u64 v[16:17], v[6:7], 0, v[0:1]
	v_lshl_add_u64 v[18:19], v[16:17], 2, s[4:5]
	s_waitcnt lgkmcnt(0)
	global_load_dwordx4 v[6:9], v[18:19], off nt
	global_load_dwordx4 v[12:15], v[18:19], off offset:16 nt
	v_lshl_add_u64 v[16:17], v[16:17], 1, s[96:97]
	s_waitcnt vmcnt(1)
	v_pk_mul_f32 v[8:9], v[8:9], s[20:21] op_sel_hi:[1,0]
	v_pk_mul_f32 v[6:7], v[6:7], s[20:21] op_sel_hi:[1,0]
	s_waitcnt vmcnt(0)
	v_pk_mul_f32 v[14:15], v[14:15], s[20:21] op_sel_hi:[1,0]
	v_pk_mul_f32 v[12:13], v[12:13], s[20:21] op_sel_hi:[1,0]
	v_pk_fma_f32 v[20:21], v[62:63], s[22:23], v[8:9] op_sel_hi:[1,0,1]
	v_pk_fma_f32 v[22:23], v[60:61], s[22:23], v[6:7] op_sel_hi:[1,0,1]
	v_pk_fma_f32 v[24:25], v[58:59], s[22:23], v[14:15] op_sel_hi:[1,0,1]
	v_pk_fma_f32 v[26:27], v[56:57], s[22:23], v[12:13] op_sel_hi:[1,0,1]
	v_cvt_pk_f16_f32 v9, v24, v25
	v_cvt_pk_f16_f32 v7, v20, v21
	v_cvt_pk_f16_f32 v8, v26, v27
	v_cvt_pk_f16_f32 v6, v22, v23
	global_store_dwordx4 v[16:17], v[6:9], off
	global_load_dwordx4 v[6:9], v[18:19], off offset:512 nt
	s_nop 0
	global_load_dwordx4 v[12:15], v[18:19], off offset:528 nt
	v_add_f32_e32 v18, v22, v23
	v_add_f32_e32 v28, v20, v21
	v_add_f32_e32 v30, v26, v27
	v_add_f32_e32 v56, v24, v25
	v_mul_f32_e32 v59, v22, v22
	v_mul_f32_e32 v23, v23, v23
	v_mul_f32_e32 v61, v20, v20
	v_mul_f32_e32 v21, v21, v21
	v_mul_f32_e32 v63, v26, v26
	v_mul_f32_e32 v27, v27, v27
	v_mul_f32_e32 v65, v24, v24
	v_mul_f32_e32 v25, v25, v25
	s_waitcnt vmcnt(1)
	v_pk_mul_f32 v[6:7], v[6:7], s[20:21] op_sel_hi:[1,0]
	s_waitcnt vmcnt(0)
	v_pk_mul_f32 v[14:15], v[14:15], s[20:21] op_sel_hi:[1,0]
	v_pk_mul_f32 v[12:13], v[12:13], s[20:21] op_sel_hi:[1,0]
	v_pk_mul_f32 v[8:9], v[8:9], s[20:21] op_sel_hi:[1,0]
	v_pk_fma_f32 v[52:53], v[52:53], s[22:23], v[6:7] op_sel_hi:[1,0,1]
	v_pk_fma_f32 v[6:7], v[50:51], s[22:23], v[14:15] op_sel_hi:[1,0,1]
	v_pk_fma_f32 v[48:49], v[48:49], s[22:23], v[12:13] op_sel_hi:[1,0,1]
	v_pk_fma_f32 v[54:55], v[54:55], s[22:23], v[8:9] op_sel_hi:[1,0,1]
	v_pk_mul_f32 v[8:9], v[6:7], v[6:7]
	v_pk_mul_f32 v[12:13], v[48:49], v[48:49]
	v_mul_f32_e32 v19, v52, v52
	v_pk_mov_b32 v[14:15], v[12:13], v[8:9] op_sel:[1,0]
	v_mov_b32_e32 v13, v9
	v_mul_f32_e32 v29, v53, v53
	v_mul_f32_e32 v31, v54, v54
	v_mul_f32_e32 v57, v55, v55
	v_mov_b32_e32 v58, v52
	v_mov_b32_e32 v22, v53
	v_mov_b32_e32 v60, v54
	v_mov_b32_e32 v20, v55
	v_mov_b32_e32 v62, v48
	v_mov_b32_e32 v26, v49
	v_mov_b32_e32 v64, v6
	v_mov_b32_e32 v24, v7
	v_pk_add_f32 v[12:13], v[14:15], v[12:13]
	v_pk_add_f32 v[8:9], v[58:59], v[22:23]
	v_pk_add_f32 v[20:21], v[60:61], v[20:21]
	v_pk_add_f32 v[22:23], v[62:63], v[26:27]
	v_pk_add_f32 v[24:25], v[64:65], v[24:25]
	v_pk_add_f32 v[18:19], v[18:19], v[28:29]
	v_pk_add_f32 v[26:27], v[30:31], v[56:57]
	v_pk_add_f32 v[12:13], v[12:13], v[12:13] op_sel_hi:[0,1]
	v_pk_add_f32 v[8:9], v[8:9], v[20:21]
	v_pk_add_f32 v[14:15], v[22:23], v[24:25]
	v_pk_add_f32 v[18:19], v[18:19], v[26:27]
	v_mov_b32_e32 v171, v13
	v_pk_add_f32 v[8:9], v[8:9], v[14:15]
	v_pk_add_f32 v[12:13], v[18:19], v[170:171]
	v_cvt_pk_f16_f32 v15, v6, v7
	v_pk_add_f32 v[8:9], v[8:9], v[12:13]
	ds_bpermute_b32 v12, v10, v8
	ds_bpermute_b32 v13, v10, v9
	v_cvt_pk_f16_f32 v14, v48, v49
	s_waitcnt lgkmcnt(0)
	v_pk_add_f32 v[6:7], v[8:9], v[12:13]
	ds_bpermute_b32 v8, v11, v6
	ds_bpermute_b32 v9, v11, v7
	v_cvt_pk_f16_f32 v13, v54, v55
	v_cvt_pk_f16_f32 v12, v52, v53
	global_store_dwordx4 v[16:17], v[12:15], off offset:256
	s_and_saveexec_b64 s[34:35], s[8:9]
	s_cbranch_execz .LBB0_493
	s_lshl_b32 s36, s6, 2
	v_lshlrev_b64 v[4:5], 8, v[4:5]
	s_ashr_i32 s37, s36, 31
	v_lshl_add_u64 v[4:5], s[0:1], 0, v[4:5]
	v_lshl_add_u64 v[4:5], s[36:37], 3, v[4:5]
	s_lshl_b32 s12, s42, 3
	s_waitcnt lgkmcnt(0)
	v_pk_add_f32 v[6:7], v[6:7], v[8:9]
	v_lshl_add_u64 v[4:5], v[4:5], 0, s[12:13]
	global_store_dwordx2 v[4:5], v[6:7], off
;     __device__ __forceinline__ void operator()(f32x4 (&acc)[2][2][4][2], const pg8::Unit& u, int wr, int wc, int fr, int fq) const {
;     ...
;                 const int row = row0 + ai * 128 + m * 16; const size_t off = (size_t)row * D + col0;
;                 float s = 0.f, q = 0.f;
; #pragma unroll
;                 for (int bj = 0; bj < 2; ++bj) {
;                     const f32x4 x0 = *(const f32x4*)(x + off + bj * 128), x1 = *(const f32x4*)(x + off + bj * 128 + 4);
;                     const f32x4 z0 = x0 * DN_ALPHA + acc[ai][bj][m][0] * ascale, z1 = x1 * DN_ALPHA + acc[ai][bj][m][1] * ascale;
;                     *(h8*)(z16 + off + bj * 128) = (h8){(_Float16)z0[0], (_Float16)z0[1], (_Float16)z0[2], (_Float16)z0[3], (_Float16)z1[0], (_Float16)z1[1], (_Float16)z1[2], (_Float16)z1[3]};
;                     s += ((z0[0] + z0[1]) + (z0[2] + z0[3])) + ((z1[0] + z1[1]) + (z1[2] + z1[3]));
;                     q += ((z0[0] * z0[0] + z0[1] * z0[1]) + (z0[2] * z0[2] + z0[3] * z0[3])) + ((z1[0] * z1[0] + z1[1] * z1[1]) + (z1[2] * z1[2] + z1[3] * z1[3]));
;                 }
;                 s += __shfl_xor(s, 16); s += __shfl_xor(s, 32); q += __shfl_xor(q, 16); q += __shfl_xor(q, 32);
;                 if (fq == 0) stats[(size_t)row * 32 + u.pn * 4 + wc] = (f32x2){s, q};
;                 asm volatile("" ::: "memory");
.LBB0_493:
	s_or_b64 exec, exec, s[34:35]
	v_add_u32_e32 v2, 0xb0, v2
	v_ashrrev_i32_e32 v3, 31, v2
	v_lshlrev_b64 v[4:5], 11, v[2:3]
	v_lshl_add_u64 v[0:1], v[4:5], 0, v[0:1]
	s_waitcnt lgkmcnt(0)
	v_lshl_add_u64 v[8:9], v[0:1], 2, s[4:5]
	global_load_dwordx4 v[4:7], v[8:9], off nt
	global_load_dwordx4 v[12:15], v[8:9], off offset:16 nt
	v_lshl_add_u64 v[16:17], v[0:1], 1, s[96:97]
	s_waitcnt vmcnt(1)
	v_pk_mul_f32 v[0:1], v[6:7], s[20:21] op_sel_hi:[1,0]
	v_pk_mul_f32 v[4:5], v[4:5], s[20:21] op_sel_hi:[1,0]
	s_waitcnt vmcnt(0)
	v_pk_mul_f32 v[6:7], v[14:15], s[20:21] op_sel_hi:[1,0]
	v_pk_mul_f32 v[12:13], v[12:13], s[20:21] op_sel_hi:[1,0]
	v_pk_fma_f32 v[0:1], v[46:47], s[22:23], v[0:1] op_sel_hi:[1,0,1]
	v_pk_fma_f32 v[18:19], v[44:45], s[22:23], v[4:5] op_sel_hi:[1,0,1]
	v_pk_fma_f32 v[20:21], v[42:43], s[22:23], v[6:7] op_sel_hi:[1,0,1]
	v_pk_fma_f32 v[22:23], v[40:41], s[22:23], v[12:13] op_sel_hi:[1,0,1]
	v_cvt_pk_f16_f32 v7, v20, v21
	v_cvt_pk_f16_f32 v5, v0, v1
	v_cvt_pk_f16_f32 v6, v22, v23
	v_cvt_pk_f16_f32 v4, v18, v19
	global_store_dwordx4 v[16:17], v[4:7], off
	global_load_dwordx4 v[4:7], v[8:9], off offset:512 nt
	s_nop 0
	global_load_dwordx4 v[12:15], v[8:9], off offset:528 nt
	v_add_f32_e32 v8, v18, v19
	v_add_f32_e32 v24, v0, v1
	v_add_f32_e32 v26, v22, v23
	v_add_f32_e32 v28, v20, v21
	v_mul_f32_e32 v31, v18, v18
	v_mul_f32_e32 v19, v19, v19
	v_mul_f32_e32 v41, v0, v0
	v_mul_f32_e32 v1, v1, v1
	v_mul_f32_e32 v43, v22, v22
	v_mul_f32_e32 v23, v23, v23
	v_mul_f32_e32 v45, v20, v20
	v_mul_f32_e32 v21, v21, v21
	s_waitcnt vmcnt(1)
	v_pk_mul_f32 v[4:5], v[4:5], s[20:21] op_sel_hi:[1,0]
	s_waitcnt vmcnt(0)
	v_pk_mul_f32 v[14:15], v[14:15], s[20:21] op_sel_hi:[1,0]
	v_pk_mul_f32 v[12:13], v[12:13], s[20:21] op_sel_hi:[1,0]
	v_pk_mul_f32 v[6:7], v[6:7], s[20:21] op_sel_hi:[1,0]
	v_pk_fma_f32 v[36:37], v[36:37], s[22:23], v[4:5] op_sel_hi:[1,0,1]
	v_pk_fma_f32 v[4:5], v[34:35], s[22:23], v[14:15] op_sel_hi:[1,0,1]
	v_pk_fma_f32 v[12:13], v[32:33], s[22:23], v[12:13] op_sel_hi:[1,0,1]
	v_pk_fma_f32 v[6:7], v[38:39], s[22:23], v[6:7] op_sel_hi:[1,0,1]
	v_pk_mul_f32 v[14:15], v[4:5], v[4:5]
	v_pk_mul_f32 v[32:33], v[12:13], v[12:13]
	v_mul_f32_e32 v9, v36, v36
	v_mul_f32_e32 v25, v37, v37
	v_mov_b32_e32 v30, v36
	v_mov_b32_e32 v18, v37
	v_mov_b32_e32 v40, v6
	v_mov_b32_e32 v0, v7
	v_mov_b32_e32 v42, v12
	v_mov_b32_e32 v22, v13
	v_mov_b32_e32 v44, v4
	v_mov_b32_e32 v20, v5
	v_pk_mov_b32 v[34:35], v[32:33], v[14:15] op_sel:[1,0]
	v_mov_b32_e32 v33, v15
	v_mul_f32_e32 v27, v6, v6
	v_mul_f32_e32 v29, v7, v7
	v_pk_add_f32 v[14:15], v[30:31], v[18:19]
	v_pk_add_f32 v[0:1], v[40:41], v[0:1]
	v_pk_add_f32 v[18:19], v[42:43], v[22:23]
	v_pk_add_f32 v[20:21], v[44:45], v[20:21]
	v_pk_add_f32 v[8:9], v[8:9], v[24:25]
	v_pk_add_f32 v[24:25], v[34:35], v[32:33]
	v_pk_add_f32 v[22:23], v[26:27], v[28:29]
	v_pk_add_f32 v[0:1], v[14:15], v[0:1]
	v_pk_add_f32 v[14:15], v[18:19], v[20:21]
	v_pk_add_f32 v[18:19], v[24:25], v[24:25] op_sel_hi:[0,1]
	v_pk_add_f32 v[8:9], v[8:9], v[22:23]
	v_mov_b32_e32 v171, v19
	v_pk_add_f32 v[0:1], v[0:1], v[14:15]
	v_pk_add_f32 v[8:9], v[8:9], v[170:171]
	v_cvt_pk_f16_f32 v7, v6, v7
	v_pk_add_f32 v[0:1], v[0:1], v[8:9]
	ds_bpermute_b32 v14, v10, v0
	ds_bpermute_b32 v15, v10, v1
	v_cvt_pk_f16_f32 v9, v4, v5
	v_cvt_pk_f16_f32 v8, v12, v13
	v_cvt_pk_f16_f32 v6, v36, v37
	global_store_dwordx4 v[16:17], v[6:9], off offset:256
	s_waitcnt lgkmcnt(0)
	v_pk_add_f32 v[0:1], v[0:1], v[14:15]
	ds_bpermute_b32 v4, v11, v0
	ds_bpermute_b32 v5, v11, v1
	s_and_saveexec_b64 s[34:35], s[8:9]
	s_cbranch_execz .LBB0_495
	s_lshl_b32 s6, s6, 2
	v_lshlrev_b64 v[2:3], 8, v[2:3]
	s_ashr_i32 s7, s6, 31
	v_lshl_add_u64 v[2:3], s[0:1], 0, v[2:3]
	v_lshl_add_u64 v[2:3], s[6:7], 3, v[2:3]
	s_lshl_b32 s12, s42, 3
	s_waitcnt lgkmcnt(0)
	v_pk_add_f32 v[0:1], v[0:1], v[4:5]
	v_lshl_add_u64 v[2:3], v[2:3], 0, s[12:13]
	global_store_dwordx2 v[2:3], v[0:1], off
